# VM2 NOMAX loops: next-step K fragment LDS reads moved from PV gaps 3-6 (2/gap) to gaps 8-15 (1/gap), lgkmcnt counts re-derived
# baseline (speedup 1.0000x reference)
.LBB0_863:
	v_lshl_add_u32 v206, s89, 1, v168
	ds_read_b64_tr_b16 v[194:195], v206 offset:24576
	ds_read_b64_tr_b16 v[196:197], v206 offset:25088
	v_add_f32_e32 v108, v80, v81
	ds_read_b128 v[246:249], v188 offset:1024
	v_add_f32_e32 v108, v82, v108
	v_add_f32_e32 v108, v83, v108
	v_add_f32_e32 v108, v84, v108
	v_add_f32_e32 v108, v85, v108
	v_cvt_pk_bf16_f32 v156, v80, v81
	v_cvt_pk_bf16_f32 v157, v82, v83
	v_mfma_f32_32x32x16_bf16 v[112:127], v[100:103], v[242:245], 0
	ds_read_b64_tr_b16 v[80:81], v206 offset:28672
	ds_read_b64_tr_b16 v[82:83], v206 offset:29184
	v_add_f32_e32 v104, v86, v108
	v_add_f32_e32 v104, v87, v104
	v_add_f32_e32 v104, v88, v104
	v_add_f32_e32 v144, v89, v104
	v_mfma_f32_32x32x16_bf16 v[96:111], v[96:99], v[242:245], 0
	v_cvt_pk_bf16_f32 v158, v84, v85
	v_cvt_pk_bf16_f32 v159, v86, v87
	ds_read_b64_tr_b16 v[84:85], v206 offset:25600
	ds_read_b64_tr_b16 v[86:87], v206 offset:26112
	ds_read_b128 v[242:245], v188 offset:2048
	v_add_f32_e32 v144, v90, v144
	v_add_f32_e32 v144, v91, v144
	v_add_f32_e32 v144, v92, v144
	v_add_f32_e32 v144, v93, v144
	v_cvt_pk_bf16_f32 v152, v88, v89
	v_cvt_pk_bf16_f32 v153, v90, v91
	s_waitcnt lgkmcnt(5)
	v_mfma_f32_32x32x16_bf16 v[112:127], v[164:167], v[246:249], v[112:127]
	ds_read_b64_tr_b16 v[88:89], v206 offset:29696
	ds_read_b64_tr_b16 v[90:91], v206 offset:30208
	v_add_f32_e32 v144, v94, v144
	v_add_f32_e32 v144, v95, v144
	v_add_f32_e32 v144, v64, v144
	v_add_f32_e32 v144, v65, v144
	v_mfma_f32_32x32x16_bf16 v[96:111], v[160:163], v[246:249], v[96:111]
	v_cvt_pk_bf16_f32 v154, v92, v93
	v_cvt_pk_bf16_f32 v155, v94, v95
	ds_read_b64_tr_b16 v[92:93], v206 offset:26624
	ds_read_b64_tr_b16 v[94:95], v206 offset:27136
	ds_read_b128 v[246:249], v188 offset:3072
	v_add_f32_e32 v144, v66, v144
	v_add_f32_e32 v144, v67, v144
	v_add_f32_e32 v144, v68, v144
	v_add_f32_e32 v144, v69, v144
	v_cvt_pk_bf16_f32 v148, v64, v65
	v_cvt_pk_bf16_f32 v149, v66, v67
	s_waitcnt lgkmcnt(5)
	v_mfma_f32_32x32x16_bf16 v[112:127], v[140:143], v[242:245], v[112:127]
	ds_read_b64_tr_b16 v[198:199], v206 offset:30720
	ds_read_b64_tr_b16 v[200:201], v206 offset:31232
	v_add_f32_e32 v140, v70, v144
	v_add_f32_e32 v140, v71, v140
	v_add_f32_e32 v140, v72, v140
	v_add_f32_e32 v140, v73, v140
	v_mfma_f32_32x32x16_bf16 v[96:111], v[136:139], v[242:245], v[96:111]
	v_cvt_pk_bf16_f32 v150, v68, v69
	v_cvt_pk_bf16_f32 v151, v70, v71
	ds_read_b64_tr_b16 v[202:203], v206 offset:27648
	ds_read_b64_tr_b16 v[204:205], v206 offset:28160
	v_add_f32_e32 v68, v74, v140
	v_add_f32_e32 v68, v75, v68
	v_add_f32_e32 v68, v76, v68
	v_add_f32_e32 v68, v77, v68
	v_cvt_pk_bf16_f32 v144, v72, v73
	v_cvt_pk_bf16_f32 v145, v74, v75
	s_waitcnt lgkmcnt(4)
	v_mfma_f32_32x32x16_bf16 v[112:127], v[132:135], v[246:249], v[112:127]
	ds_read_b64_tr_b16 v[72:73], v206 offset:31744
	ds_read_b64_tr_b16 v[74:75], v206 offset:32256
	v_add_f32_e32 v68, v78, v68
	v_add_f32_e32 v68, v79, v68
	v_add_f32_e32 v68, 0, v68
	v_cvt_pk_bf16_f32 v146, v76, v77
	v_mfma_f32_32x32x16_bf16 v[96:111], v[128:131], v[246:249], v[96:111]
	v_cvt_pk_bf16_f32 v147, v78, v79
	s_add_i32 s88, s87, s35
	v_lshl_add_u64 v[64:65], v[180:181], 0, s[54:55]
	s_mov_b32 s89, m0
	s_mov_b32 m0, s88
	s_nop 0
	global_load_lds_dwordx4 v[64:65], off
	s_mov_b32 m0, s89
	s_lshl_b32 s88, s86, 1
	v_lshl_add_u64 v[64:65], v[178:179], 0, s[54:55]
	s_add_i32 s88, s88, s16
	s_mov_b32 s89, m0
	s_mov_b32 m0, s88
	s_nop 0
	global_load_lds_dwordx4 v[64:65], off
	s_mov_b32 m0, s89
	v_lshl_add_u64 v[64:65], v[176:177], 0, s[54:55]
	s_addk_i32 s88, 0x2000
	s_mov_b32 s89, m0
	s_mov_b32 m0, s88
	s_nop 0
	global_load_lds_dwordx4 v[64:65], off
	s_mov_b32 m0, s89
	v_add_f32_e32 v193, v193, v68
	v_mfma_f32_32x32x16_bf16 v[48:63], v[156:159], v[194:197], v[48:63]
	ds_read_b64_tr_b16 v[76:77], v206 offset:32768
	ds_read_b64_tr_b16 v[78:79], v206 offset:33280
	v_exp_f32_e32 v112, v112
	v_exp_f32_e32 v113, v113
	v_mfma_f32_32x32x16_bf16 v[32:47], v[156:159], v[80:83], v[32:47]
	ds_read_b64_tr_b16 v[194:195], v206 offset:36864
	ds_read_b64_tr_b16 v[196:197], v206 offset:37376
	v_exp_f32_e32 v114, v114
	v_exp_f32_e32 v115, v115
	v_add_u32_e32 v128, s86, v189
	v_mfma_f32_32x32x16_bf16 v[48:63], v[152:155], v[84:87], v[48:63]
	ds_read_b64_tr_b16 v[80:81], v206 offset:33792
	ds_read_b64_tr_b16 v[82:83], v206 offset:34304
	v_exp_f32_e32 v116, v116
	v_exp_f32_e32 v117, v117
	v_mfma_f32_32x32x16_bf16 v[32:47], v[152:155], v[88:91], v[32:47]
	ds_read_b64_tr_b16 v[84:85], v206 offset:37888
	ds_read_b64_tr_b16 v[86:87], v206 offset:38400
	v_exp_f32_e32 v118, v118
	v_exp_f32_e32 v119, v119
	v_mfma_f32_32x32x16_bf16 v[48:63], v[148:151], v[92:95], v[48:63]
	ds_read_b64_tr_b16 v[88:89], v206 offset:34816
	ds_read_b64_tr_b16 v[90:91], v206 offset:35328
	v_exp_f32_e32 v120, v120
	v_exp_f32_e32 v121, v121
	s_waitcnt lgkmcnt(10)
	v_mfma_f32_32x32x16_bf16 v[32:47], v[148:151], v[198:201], v[32:47]
	ds_read_b64_tr_b16 v[92:93], v206 offset:38912
	ds_read_b64_tr_b16 v[94:95], v206 offset:39424
	v_exp_f32_e32 v122, v122
	v_exp_f32_e32 v123, v123
	v_mfma_f32_32x32x16_bf16 v[48:63], v[144:147], v[202:205], v[48:63]
	ds_read_b64_tr_b16 v[198:199], v206 offset:35840
	ds_read_b64_tr_b16 v[200:201], v206 offset:36352
	v_exp_f32_e32 v124, v124
	v_exp_f32_e32 v125, v125
	v_mfma_f32_32x32x16_bf16 v[32:47], v[144:147], v[72:75], v[32:47]
	ds_read_b64_tr_b16 v[202:203], v206 offset:39936
	ds_read_b64_tr_b16 v[204:205], v206 offset:40448
	v_exp_f32_e32 v126, v126
	v_exp_f32_e32 v127, v127
	ds_read_b128 v[68:71], v128
	s_waitcnt lgkmcnt(13)
	v_mfma_f32_32x32x16_bf16 v[16:31], v[156:159], v[76:79], v[16:31]
	v_exp_f32_e32 v96, v96
	v_exp_f32_e32 v97, v97
	ds_read_b128 v[64:67], v128 offset:512
	v_mfma_f32_32x32x16_bf16 v[0:15], v[156:159], v[194:197], v[0:15]
	v_exp_f32_e32 v98, v98
	v_exp_f32_e32 v99, v99
	ds_read_b128 v[164:167], v128 offset:2048
	s_waitcnt lgkmcnt(11)
	v_mfma_f32_32x32x16_bf16 v[16:31], v[152:155], v[80:83], v[16:31]
	v_exp_f32_e32 v100, v100
	v_exp_f32_e32 v101, v101
	ds_read_b128 v[140:143], v128 offset:2560
	v_mfma_f32_32x32x16_bf16 v[0:15], v[152:155], v[84:87], v[0:15]
	v_exp_f32_e32 v102, v102
	v_exp_f32_e32 v103, v103
	ds_read_b128 v[160:163], v128 offset:4096
	s_waitcnt lgkmcnt(9)
	v_mfma_f32_32x32x16_bf16 v[16:31], v[148:151], v[88:91], v[16:31]
	v_exp_f32_e32 v104, v104
	v_exp_f32_e32 v105, v105
	ds_read_b128 v[132:135], v128 offset:4608
	v_mfma_f32_32x32x16_bf16 v[0:15], v[148:151], v[92:95], v[0:15]
	v_exp_f32_e32 v106, v106
	v_exp_f32_e32 v107, v107
	ds_read_b128 v[136:139], v128 offset:6144
	s_waitcnt lgkmcnt(7)
	v_mfma_f32_32x32x16_bf16 v[16:31], v[144:147], v[198:201], v[16:31]
	v_exp_f32_e32 v108, v108
	v_exp_f32_e32 v109, v109
	ds_read_b128 v[128:131], v128 offset:6656
	v_mfma_f32_32x32x16_bf16 v[0:15], v[144:147], v[202:205], v[0:15]
	ds_read_b128 v[242:245], v188
	v_exp_f32_e32 v110, v110
	v_exp_f32_e32 v111, v111
	s_waitcnt vmcnt(3) lgkmcnt(0)
	s_barrier
	s_add_i32 s88, s86, 0x2000
	s_cmpk_lg_i32 s86, 0x4000
	s_cselect_b32 s88, s88, 0
	v_lshl_add_u32 v206, s87, 1, v168
	ds_read_b64_tr_b16 v[194:195], v206 offset:24576
	ds_read_b64_tr_b16 v[196:197], v206 offset:25088
	ds_read_b128 v[246:249], v188 offset:1024
	v_add_f32_e32 v76, v112, v113
	v_add_f32_e32 v76, v114, v76
	v_add_f32_e32 v76, v115, v76
	v_add_f32_e32 v76, v116, v76
	v_mfma_f32_32x32x16_bf16 v[80:95], v[68:71], v[242:245], 0
	v_add_f32_e32 v76, v117, v76
	v_cvt_pk_bf16_f32 v156, v112, v113
	v_cvt_pk_bf16_f32 v157, v114, v115
	ds_read_b64_tr_b16 v[112:113], v206 offset:28672
	ds_read_b64_tr_b16 v[114:115], v206 offset:29184
	v_add_f32_e32 v72, v118, v76
	v_add_f32_e32 v72, v119, v72
	v_add_f32_e32 v72, v120, v72
	v_add_f32_e32 v144, v121, v72
	v_mfma_f32_32x32x16_bf16 v[64:79], v[64:67], v[242:245], 0
	v_cvt_pk_bf16_f32 v158, v116, v117
	v_cvt_pk_bf16_f32 v159, v118, v119
	ds_read_b64_tr_b16 v[116:117], v206 offset:25600
	ds_read_b64_tr_b16 v[118:119], v206 offset:26112
	ds_read_b128 v[242:245], v188 offset:2048
	v_add_f32_e32 v144, v122, v144
	v_add_f32_e32 v144, v123, v144
	v_add_f32_e32 v144, v124, v144
	v_add_f32_e32 v144, v125, v144
	s_waitcnt lgkmcnt(5)
	v_mfma_f32_32x32x16_bf16 v[80:95], v[164:167], v[246:249], v[80:95]
	v_cvt_pk_bf16_f32 v152, v120, v121
	v_cvt_pk_bf16_f32 v153, v122, v123
	ds_read_b64_tr_b16 v[120:121], v206 offset:29696
	ds_read_b64_tr_b16 v[122:123], v206 offset:30208
	v_add_f32_e32 v144, v126, v144
	v_add_f32_e32 v144, v127, v144
	v_add_f32_e32 v144, v96, v144
	v_add_f32_e32 v144, v97, v144
	v_mfma_f32_32x32x16_bf16 v[64:79], v[140:143], v[246:249], v[64:79]
	v_cvt_pk_bf16_f32 v154, v124, v125
	v_cvt_pk_bf16_f32 v155, v126, v127
	ds_read_b64_tr_b16 v[124:125], v206 offset:26624
	ds_read_b64_tr_b16 v[126:127], v206 offset:27136
	ds_read_b128 v[246:249], v188 offset:3072
	v_add_f32_e32 v144, v98, v144
	v_add_f32_e32 v144, v99, v144
	v_add_f32_e32 v144, v100, v144
	v_add_f32_e32 v144, v101, v144
	s_waitcnt lgkmcnt(5)
	v_mfma_f32_32x32x16_bf16 v[80:95], v[160:163], v[242:245], v[80:95]
	v_cvt_pk_bf16_f32 v148, v96, v97
	v_cvt_pk_bf16_f32 v149, v98, v99
	ds_read_b64_tr_b16 v[198:199], v206 offset:30720
	ds_read_b64_tr_b16 v[200:201], v206 offset:31232
	v_add_f32_e32 v140, v102, v144
	v_add_f32_e32 v140, v103, v140
	v_add_f32_e32 v140, v104, v140
	v_add_f32_e32 v140, v105, v140
	v_mfma_f32_32x32x16_bf16 v[64:79], v[132:135], v[242:245], v[64:79]
	v_cvt_pk_bf16_f32 v150, v100, v101
	v_cvt_pk_bf16_f32 v151, v102, v103
	ds_read_b64_tr_b16 v[202:203], v206 offset:27648
	ds_read_b64_tr_b16 v[204:205], v206 offset:28160
	v_add_f32_e32 v100, v106, v140
	v_add_f32_e32 v100, v107, v100
	v_add_f32_e32 v100, v108, v100
	v_add_f32_e32 v100, v109, v100
	s_waitcnt lgkmcnt(4)
	v_mfma_f32_32x32x16_bf16 v[80:95], v[136:139], v[246:249], v[80:95]
	v_cvt_pk_bf16_f32 v144, v104, v105
	v_cvt_pk_bf16_f32 v145, v106, v107
	ds_read_b64_tr_b16 v[104:105], v206 offset:31744
	ds_read_b64_tr_b16 v[106:107], v206 offset:32256
	v_add_f32_e32 v100, v110, v100
	v_add_f32_e32 v100, v111, v100
	v_add_f32_e32 v100, 0, v100
	v_cvt_pk_bf16_f32 v146, v108, v109
	v_mfma_f32_32x32x16_bf16 v[64:79], v[128:131], v[246:249], v[64:79]
	v_cvt_pk_bf16_f32 v147, v110, v111
	s_add_i32 s87, s86, s35
	s_mov_b32 s89, m0
	s_mov_b32 m0, s87
	s_nop 0
	global_load_lds_dwordx4 v[180:181], off
	s_mov_b32 m0, s89
	s_lshl_b32 s87, s88, 1
	s_add_i32 s87, s87, s16
	s_mov_b32 s89, m0
	s_mov_b32 m0, s87
	s_nop 0
	global_load_lds_dwordx4 v[178:179], off
	s_mov_b32 m0, s89
	s_addk_i32 s87, 0x2000
	s_mov_b32 s89, m0
	s_mov_b32 m0, s87
	s_nop 0
	global_load_lds_dwordx4 v[176:177], off
	s_mov_b32 m0, s89
	v_add_f32_e32 v193, v193, v100
	v_mfma_f32_32x32x16_bf16 v[48:63], v[156:159], v[194:197], v[48:63]
	ds_read_b64_tr_b16 v[108:109], v206 offset:32768
	ds_read_b64_tr_b16 v[110:111], v206 offset:33280
	v_exp_f32_e32 v80, v80
	v_exp_f32_e32 v81, v81
	v_mfma_f32_32x32x16_bf16 v[32:47], v[156:159], v[112:115], v[32:47]
	ds_read_b64_tr_b16 v[194:195], v206 offset:36864
	ds_read_b64_tr_b16 v[196:197], v206 offset:37376
	v_exp_f32_e32 v82, v82
	v_exp_f32_e32 v83, v83
	v_add_u32_e32 v128, s88, v189
	v_mfma_f32_32x32x16_bf16 v[48:63], v[152:155], v[116:119], v[48:63]
	ds_read_b64_tr_b16 v[112:113], v206 offset:33792
	ds_read_b64_tr_b16 v[114:115], v206 offset:34304
	v_exp_f32_e32 v84, v84
	v_exp_f32_e32 v85, v85
	v_mfma_f32_32x32x16_bf16 v[32:47], v[152:155], v[120:123], v[32:47]
	ds_read_b64_tr_b16 v[116:117], v206 offset:37888
	ds_read_b64_tr_b16 v[118:119], v206 offset:38400
	v_exp_f32_e32 v86, v86
	v_exp_f32_e32 v87, v87
	v_mfma_f32_32x32x16_bf16 v[48:63], v[148:151], v[124:127], v[48:63]
	ds_read_b64_tr_b16 v[120:121], v206 offset:34816
	ds_read_b64_tr_b16 v[122:123], v206 offset:35328
	v_exp_f32_e32 v88, v88
	v_exp_f32_e32 v89, v89
	s_waitcnt lgkmcnt(10)
	v_mfma_f32_32x32x16_bf16 v[32:47], v[148:151], v[198:201], v[32:47]
	ds_read_b64_tr_b16 v[124:125], v206 offset:38912
	ds_read_b64_tr_b16 v[126:127], v206 offset:39424
	v_exp_f32_e32 v90, v90
	v_exp_f32_e32 v91, v91
	v_mfma_f32_32x32x16_bf16 v[48:63], v[144:147], v[202:205], v[48:63]
	ds_read_b64_tr_b16 v[198:199], v206 offset:35840
	ds_read_b64_tr_b16 v[200:201], v206 offset:36352
	v_exp_f32_e32 v92, v92
	v_exp_f32_e32 v93, v93
	v_mfma_f32_32x32x16_bf16 v[32:47], v[144:147], v[104:107], v[32:47]
	ds_read_b64_tr_b16 v[202:203], v206 offset:39936
	ds_read_b64_tr_b16 v[204:205], v206 offset:40448
	v_exp_f32_e32 v94, v94
	v_exp_f32_e32 v95, v95
	ds_read_b128 v[100:103], v128
	s_waitcnt lgkmcnt(13)
	v_mfma_f32_32x32x16_bf16 v[16:31], v[156:159], v[108:111], v[16:31]
	v_exp_f32_e32 v64, v64
	v_exp_f32_e32 v65, v65
	ds_read_b128 v[96:99], v128 offset:512
	v_mfma_f32_32x32x16_bf16 v[0:15], v[156:159], v[194:197], v[0:15]
	v_exp_f32_e32 v66, v66
	v_exp_f32_e32 v67, v67
	ds_read_b128 v[164:167], v128 offset:2048
	s_waitcnt lgkmcnt(11)
	v_mfma_f32_32x32x16_bf16 v[16:31], v[152:155], v[112:115], v[16:31]
	v_exp_f32_e32 v68, v68
	v_exp_f32_e32 v69, v69
	ds_read_b128 v[160:163], v128 offset:2560
	v_mfma_f32_32x32x16_bf16 v[0:15], v[152:155], v[116:119], v[0:15]
	v_exp_f32_e32 v70, v70
	v_exp_f32_e32 v71, v71
	ds_read_b128 v[140:143], v128 offset:4096
	s_waitcnt lgkmcnt(9)
	v_mfma_f32_32x32x16_bf16 v[16:31], v[148:151], v[120:123], v[16:31]
	v_exp_f32_e32 v72, v72
	v_exp_f32_e32 v73, v73
	ds_read_b128 v[136:139], v128 offset:4608
	v_mfma_f32_32x32x16_bf16 v[0:15], v[148:151], v[124:127], v[0:15]
	v_exp_f32_e32 v74, v74
	v_exp_f32_e32 v75, v75
	ds_read_b128 v[132:135], v128 offset:6144
	s_waitcnt lgkmcnt(7)
	v_mfma_f32_32x32x16_bf16 v[16:31], v[144:147], v[198:201], v[16:31]
	v_exp_f32_e32 v76, v76
	v_exp_f32_e32 v77, v77
	ds_read_b128 v[128:131], v128 offset:6656
	v_mfma_f32_32x32x16_bf16 v[0:15], v[144:147], v[202:205], v[0:15]
	ds_read_b128 v[242:245], v188
	v_exp_f32_e32 v78, v78
	v_exp_f32_e32 v79, v79
	s_add_i32 s90, s88, 0x2000
	s_waitcnt vmcnt(3) lgkmcnt(0)
	s_barrier
; #define WAIT_BAR(N) asm volatile("s_waitcnt vmcnt(" #N ") lgkmcnt(0)\n\ts_barrier":::"memory")
;   #define DMA_K(t,slot) glds16(ksrc+(long)(t)*KVBLK*KVP,(unsigned)__builtin_amdgcn_readfirstlane(kdst+(slot)))
;   #define DMA_V(t,slot) do{ glds16(vsrc+(long)(t)*KVBLK*KVP,(unsigned)__builtin_amdgcn_readfirstlane(vdst+VM*(slot))); if constexpr(VM==2) glds16(vsrc+64+(long)(t)*KVBLK*KVP,(unsigned)__builtin_amdgcn_readfirstlane(vdst+VM*(slot)+8192)); }while(0)
;   #define RESC() do{ if(!NOMAX&&resc){ asm volatile("s_waitcnt lgkmcnt(0)":::"memory"); \
;       _Pragma("unroll") for(int d_=0;d_<2*VM;++d_) _Pragma("unroll") for(int r=0;r<16;++r)o[d_][r]*=wsf[crow(r,hi)]; } }while(0)
;   #define ROT() do{sl_prev=sl_cur;sl_cur=sl_next;sl_next=(sl_next==(NSLOT-1)*SLOTB)?0:sl_next+SLOTB;}while(0)
;   #define ENDW(tt) do{ if((tt)+3<NT){ if constexpr(VM==2){WAIT_BAR(3);}else{WAIT_BAR(2);} } else if((tt)+2<NT){ if constexpr(VM==2){WAIT_BAR(2);}else{WAIT_BAR(1);} } else {WAIT_BAR(0);} }while(0)
; template<int THRL,int VM,bool NOMAX> __device__ __forceinline__ void attn_unit(const bf16*Qb,const bf16*__restrict__ Kh,const bf16*__restrict__ Vh,bf16*Ob,const int NT,const int sp,float*wscr,char*shm){
;     ...
;   DMA_K(2,2*SLOTB);
;   WAIT_BAR(3);
;   qkt(pA0,pA1,Kbase,qr,negm,r32,hi);asm volatile("s_nop 15\n\ts_nop 7":"+v"(pA0),"+v"(pA1));
;   START(pA0,pA1);
;   _Pragma("unroll") for(int r=0;r<16;++r)pA1[r]=__builtin_amdgcn_exp2f(pA1[r]);
;   WAIT_BAR(0);
;   DMA_K(3,0);DMA_V(1,SLOTB);
;   ROT();
;   kload8(kf,kp0+sl_cur);
;   if constexpr(VM==2){WAIT_BAR(3);}else{WAIT_BAR(2);}
;   s16x4 vlo[8],vhi[8]; u32x4 pw0,pw1,pw2,pw3;
;     ...
;   int t=1;
;   for(;t+5<NT;t+=2){
;     STEP(pB0,pB1,pA0,pA1,t,true,true,true);     if constexpr(VM==2){WAIT_BAR(3);}else{WAIT_BAR(2);} RESC(); ROT();
;     STEP(pA0,pA1,pB0,pB1,t+1,true,true,true);   if constexpr(VM==2){WAIT_BAR(3);}else{WAIT_BAR(2);} RESC(); ROT();
;   }
;     ...
;   for(;t+1<NT;t+=2){
;     STEP(pB0,pB1,pA0,pA1,t,(t+3<NT),(t+1<NT),(t+1<NT));       ENDW(t);   RESC(); ROT();
;     STEP(pA0,pA1,pB0,pB1,t+1,(t+4<NT),(t+2<NT),(t+2<NT));     ENDW(t+1); RESC(); ROT();
	s_cmpk_lg_i32 s88, 0x4000
	s_mov_b32 s89, s86
	s_cselect_b32 s86, s90, 0
	s_add_i32 s85, s85, 2
	v_lshl_add_u64 v[176:177], v[176:177], 0, s[56:57]
	v_lshl_add_u64 v[178:179], v[178:179], 0, s[56:57]
	v_lshl_add_u64 v[180:181], v[180:181], 0, s[56:57]
	s_mov_b32 s87, s88
	s_cmpk_lt_u32 s85, 0x79
	s_cbranch_scc1 .LBB0_863
	s_and_b32 s34, s34, 0x3fffffc0
	s_lshl_b32 s34, s34, 2
	s_add_i32 s34, s34, 0
	s_add_i32 s34, s34, 0x12000
	s_cmp_lg_u32 0, -1
	s_cselect_b32 s85, 0, 0
	s_add_i32 s86, s85, 0x6000
	v_add_u32_e32 v104, s86, v191
	v_add3_u32 v176, v104, v190, v192
	v_add_u32_e32 v177, 0x6000, v168
	ds_read_b64_tr_b16 v[178:179], v168 offset:57344
	ds_read_b64_tr_b16 v[180:181], v168 offset:57856
	v_add_f32_e32 v108, v80, v81
	ds_read_b128 v[104:107], v188
	v_add_f32_e32 v108, v82, v108
	v_add_f32_e32 v108, v83, v108
	v_add_f32_e32 v108, v84, v108
	v_add_f32_e32 v108, v85, v108
	v_cvt_pk_bf16_f32 v156, v80, v81
	v_cvt_pk_bf16_f32 v157, v82, v83
	s_waitcnt lgkmcnt(0)
	v_mfma_f32_32x32x16_bf16 v[112:127], v[100:103], v[104:107], 0
	ds_read_b64_tr_b16 v[80:81], v168 offset:61440
	ds_read_b64_tr_b16 v[82:83], v168 offset:61952
	ds_read_b128 v[100:103], v188
	v_add_f32_e32 v104, v86, v108
	v_add_f32_e32 v104, v87, v104
	v_add_f32_e32 v104, v88, v104
	v_add_f32_e32 v144, v89, v104
	v_cvt_pk_bf16_f32 v158, v84, v85
	v_cvt_pk_bf16_f32 v159, v86, v87
	s_waitcnt lgkmcnt(0)
	v_mfma_f32_32x32x16_bf16 v[96:111], v[96:99], v[100:103], 0
	ds_read_b64_tr_b16 v[84:85], v168 offset:58368
	ds_read_b64_tr_b16 v[86:87], v168 offset:58880
	ds_read_b128 v[194:197], v188 offset:1024
	v_add_f32_e32 v144, v90, v144
	v_add_f32_e32 v144, v91, v144
	v_add_f32_e32 v144, v92, v144
	v_add_f32_e32 v144, v93, v144
	v_cvt_pk_bf16_f32 v152, v88, v89
	v_cvt_pk_bf16_f32 v153, v90, v91
	s_waitcnt lgkmcnt(0)
	v_mfma_f32_32x32x16_bf16 v[112:127], v[164:167], v[194:197], v[112:127]
	ds_read_b64_tr_b16 v[88:89], v168 offset:62464
	ds_read_b64_tr_b16 v[90:91], v168 offset:62976
	ds_read_b128 v[164:167], v188 offset:1024
	v_add_f32_e32 v144, v94, v144
	v_add_f32_e32 v144, v95, v144
	v_add_f32_e32 v144, v64, v144
	v_add_f32_e32 v144, v65, v144
	v_cvt_pk_bf16_f32 v154, v92, v93
	v_cvt_pk_bf16_f32 v155, v94, v95
	s_waitcnt lgkmcnt(0)
	v_mfma_f32_32x32x16_bf16 v[96:111], v[160:163], v[164:167], v[96:111]
	ds_read_b64_tr_b16 v[194:195], v168 offset:59392
	ds_read_b64_tr_b16 v[196:197], v168 offset:59904
	ds_read_b128 v[92:95], v188 offset:2048
	v_add_f32_e32 v144, v66, v144
	v_add_f32_e32 v144, v67, v144
	v_add_f32_e32 v144, v68, v144
	v_add_f32_e32 v144, v69, v144
	v_cvt_pk_bf16_f32 v148, v64, v65
	v_cvt_pk_bf16_f32 v149, v66, v67
	s_waitcnt lgkmcnt(0)
	v_mfma_f32_32x32x16_bf16 v[112:127], v[140:143], v[92:95], v[112:127]
	ds_read_b64_tr_b16 v[140:141], v168 offset:63488
	ds_read_b64_tr_b16 v[142:143], v168 offset:64000
	ds_read_b128 v[64:67], v188 offset:2048
	v_add_f32_e32 v92, v70, v144
	v_add_f32_e32 v92, v71, v92
	v_add_f32_e32 v92, v72, v92
	v_add_f32_e32 v92, v73, v92
	v_cvt_pk_bf16_f32 v150, v68, v69
	v_cvt_pk_bf16_f32 v151, v70, v71
	s_waitcnt lgkmcnt(0)
	v_mfma_f32_32x32x16_bf16 v[96:111], v[136:139], v[64:67], v[96:111]
	ds_read_b64_tr_b16 v[136:137], v168 offset:60416
	ds_read_b64_tr_b16 v[138:139], v168 offset:60928
	ds_read_b128 v[64:67], v188 offset:3072
	v_add_f32_e32 v68, v74, v92
	v_add_f32_e32 v68, v75, v68
	v_add_f32_e32 v68, v76, v68
	v_add_f32_e32 v68, v77, v68
	v_cvt_pk_bf16_f32 v144, v72, v73
	v_cvt_pk_bf16_f32 v145, v74, v75
	s_waitcnt lgkmcnt(0)
	v_mfma_f32_32x32x16_bf16 v[112:127], v[132:135], v[64:67], v[112:127]
	ds_read_b64_tr_b16 v[72:73], v168 offset:64512
	ds_read_b64_tr_b16 v[74:75], v168 offset:65024
	ds_read_b128 v[64:67], v188 offset:3072
	v_add_f32_e32 v68, v78, v68
	v_add_f32_e32 v68, v79, v68
	v_add_f32_e32 v68, 0, v68
	v_cvt_pk_bf16_f32 v146, v76, v77
	v_cvt_pk_bf16_f32 v147, v78, v79
	s_waitcnt lgkmcnt(0)
	v_mfma_f32_32x32x16_bf16 v[96:111], v[128:131], v[64:67], v[96:111]
	v_lshl_add_u64 v[64:65], v[174:175], 0, s[58:59]
	s_mov_b32 s86, m0
	s_mov_b32 m0, s35
	s_nop 0
	global_load_lds_dwordx4 v[64:65], off
	s_mov_b32 m0, s86
	s_add_i32 s85, s85, s17
	v_lshl_add_u64 v[64:65], v[170:171], 0, s[60:61]
	s_add_i32 s17, s85, 0xa000
	s_mov_b32 s35, m0
	s_mov_b32 m0, s17
	s_nop 0
	global_load_lds_dwordx4 v[64:65], off
	s_mov_b32 m0, s35
	v_lshl_add_u64 v[64:65], v[172:173], 0, s[60:61]
	s_add_i32 s35, s17, 0x2000
	s_mov_b32 s86, m0
	s_mov_b32 m0, s35
	s_nop 0
	global_load_lds_dwordx4 v[64:65], off
	s_mov_b32 m0, s86
	v_add_f32_e32 v198, v193, v68
	v_mfma_f32_32x32x16_bf16 v[48:63], v[156:159], v[178:181], v[48:63]
	ds_read_b64_tr_b16 v[76:77], v177 offset:40960
	ds_read_b64_tr_b16 v[78:79], v177 offset:41472
	v_exp_f32_e32 v112, v112
	v_exp_f32_e32 v113, v113
	v_mfma_f32_32x32x16_bf16 v[32:47], v[156:159], v[80:83], v[32:47]
	ds_read_b64_tr_b16 v[128:129], v177 offset:45056
	ds_read_b64_tr_b16 v[130:131], v177 offset:45568
	v_exp_f32_e32 v114, v114
	v_exp_f32_e32 v115, v115
	ds_read_b128 v[68:71], v189 offset:8192
	ds_read_b128 v[64:67], v189 offset:8704
	v_mfma_f32_32x32x16_bf16 v[48:63], v[152:155], v[84:87], v[48:63]
	ds_read_b64_tr_b16 v[132:133], v177 offset:41984
	ds_read_b64_tr_b16 v[134:135], v177 offset:42496
	v_exp_f32_e32 v116, v116
	v_exp_f32_e32 v117, v117
	ds_read_b128 v[164:167], v189 offset:10240
	ds_read_b128 v[92:95], v189 offset:10752
	v_mfma_f32_32x32x16_bf16 v[32:47], v[152:155], v[88:91], v[32:47]
	ds_read_b64_tr_b16 v[178:179], v177 offset:46080
	ds_read_b64_tr_b16 v[180:181], v177 offset:46592
	v_exp_f32_e32 v118, v118
	v_exp_f32_e32 v119, v119
	ds_read_b128 v[160:163], v189 offset:12288
	ds_read_b128 v[84:87], v189 offset:12800
	v_mfma_f32_32x32x16_bf16 v[48:63], v[148:151], v[194:197], v[48:63]
	ds_read_b64_tr_b16 v[190:191], v177 offset:43008
	ds_read_b64_tr_b16 v[192:193], v177 offset:43520
	v_exp_f32_e32 v120, v120
	v_exp_f32_e32 v121, v121
	ds_read_b128 v[88:91], v189 offset:14336
	ds_read_b128 v[80:83], v189 offset:14848
	v_mfma_f32_32x32x16_bf16 v[32:47], v[148:151], v[140:143], v[32:47]
	ds_read_b64_tr_b16 v[194:195], v177 offset:47104
	ds_read_b64_tr_b16 v[196:197], v177 offset:47616
	v_exp_f32_e32 v122, v122
	v_exp_f32_e32 v123, v123
	v_mfma_f32_32x32x16_bf16 v[48:63], v[144:147], v[136:139], v[48:63]
	ds_read_b64_tr_b16 v[140:141], v177 offset:44032
	ds_read_b64_tr_b16 v[142:143], v177 offset:44544
	v_exp_f32_e32 v124, v124
	v_exp_f32_e32 v125, v125
	v_mfma_f32_32x32x16_bf16 v[32:47], v[144:147], v[72:75], v[32:47]
	ds_read_b64_tr_b16 v[136:137], v177 offset:48128
	ds_read_b64_tr_b16 v[138:139], v177 offset:48640
	v_exp_f32_e32 v126, v126
	v_exp_f32_e32 v127, v127
	s_waitcnt lgkmcnt(14)
; #define WAIT_BAR(N) asm volatile("s_waitcnt vmcnt(" #N ") lgkmcnt(0)\n\ts_barrier":::"memory")
;   #define RESC() do{ if(!NOMAX&&resc){ asm volatile("s_waitcnt lgkmcnt(0)":::"memory"); \
;       _Pragma("unroll") for(int d_=0;d_<2*VM;++d_) _Pragma("unroll") for(int r=0;r<16;++r)o[d_][r]*=wsf[crow(r,hi)]; } }while(0)
;   #define ROT() do{sl_prev=sl_cur;sl_cur=sl_next;sl_next=(sl_next==(NSLOT-1)*SLOTB)?0:sl_next+SLOTB;}while(0)
;   #define ENDW(tt) do{ if((tt)+3<NT){ if constexpr(VM==2){WAIT_BAR(3);}else{WAIT_BAR(2);} } else if((tt)+2<NT){ if constexpr(VM==2){WAIT_BAR(2);}else{WAIT_BAR(1);} } else {WAIT_BAR(0);} }while(0)
; template<int THRL,int VM,bool NOMAX> __device__ __forceinline__ void attn_unit(const bf16*Qb,const bf16*__restrict__ Kh,const bf16*__restrict__ Vh,bf16*Ob,const int NT,const int sp,float*wscr,char*shm){
;     ...
;   int t=1;
;   for(;t+5<NT;t+=2){
;     STEP(pB0,pB1,pA0,pA1,t,true,true,true);     if constexpr(VM==2){WAIT_BAR(3);}else{WAIT_BAR(2);} RESC(); ROT();
;     STEP(pA0,pA1,pB0,pB1,t+1,true,true,true);   if constexpr(VM==2){WAIT_BAR(3);}else{WAIT_BAR(2);} RESC(); ROT();
;   }
;     ...
;   for(;t+1<NT;t+=2){
;     STEP(pB0,pB1,pA0,pA1,t,(t+3<NT),(t+1<NT),(t+1<NT));       ENDW(t);   RESC(); ROT();
;     STEP(pA0,pA1,pB0,pB1,t+1,(t+4<NT),(t+2<NT),(t+2<NT));     ENDW(t+1); RESC(); ROT();
	v_mfma_f32_32x32x16_bf16 v[16:31], v[156:159], v[76:79], v[16:31]
	v_exp_f32_e32 v96, v96
	v_exp_f32_e32 v97, v97
	v_mfma_f32_32x32x16_bf16 v[0:15], v[156:159], v[128:131], v[0:15]
	v_exp_f32_e32 v98, v98
	v_exp_f32_e32 v99, v99
	v_mfma_f32_32x32x16_bf16 v[16:31], v[152:155], v[132:135], v[16:31]
	v_exp_f32_e32 v100, v100
	v_exp_f32_e32 v101, v101
	s_waitcnt lgkmcnt(12)
	v_mfma_f32_32x32x16_bf16 v[0:15], v[152:155], v[178:181], v[0:15]
	v_exp_f32_e32 v102, v102
	v_exp_f32_e32 v103, v103
	s_waitcnt lgkmcnt(8)
	v_mfma_f32_32x32x16_bf16 v[16:31], v[148:151], v[190:193], v[16:31]
	v_exp_f32_e32 v104, v104
	v_exp_f32_e32 v105, v105
	s_waitcnt lgkmcnt(4)
	v_mfma_f32_32x32x16_bf16 v[0:15], v[148:151], v[194:197], v[0:15]
	v_exp_f32_e32 v106, v106
	v_exp_f32_e32 v107, v107
	s_waitcnt lgkmcnt(2)
	v_mfma_f32_32x32x16_bf16 v[16:31], v[144:147], v[140:143], v[16:31]
	v_exp_f32_e32 v108, v108
	v_exp_f32_e32 v109, v109
	s_waitcnt lgkmcnt(0)
	v_mfma_f32_32x32x16_bf16 v[0:15], v[144:147], v[136:139], v[0:15]
	v_exp_f32_e32 v110, v110
	v_exp_f32_e32 v111, v111
	s_waitcnt vmcnt(3) lgkmcnt(0)
	s_barrier
	ds_read_b64_tr_b16 v[178:179], v168 offset:24576
	ds_read_b64_tr_b16 v[180:181], v168 offset:25088
	v_add_f32_e32 v76, v112, v113
	ds_read_b128 v[72:75], v188
	v_add_f32_e32 v76, v114, v76
	v_add_f32_e32 v76, v115, v76
	v_add_f32_e32 v76, v116, v76
	v_add_f32_e32 v76, v117, v76
	v_cvt_pk_bf16_f32 v156, v112, v113
	v_cvt_pk_bf16_f32 v157, v114, v115
	s_waitcnt lgkmcnt(0)
	v_mfma_f32_32x32x16_bf16 v[128:143], v[68:71], v[72:75], 0
	ds_read_b64_tr_b16 v[112:113], v168 offset:28672
	ds_read_b64_tr_b16 v[114:115], v168 offset:29184
	ds_read_b128 v[68:71], v188
	v_add_f32_e32 v72, v118, v76
	v_add_f32_e32 v72, v119, v72
	v_add_f32_e32 v72, v120, v72
	v_add_f32_e32 v144, v121, v72
	s_waitcnt lgkmcnt(0)
	v_mfma_f32_32x32x16_bf16 v[64:79], v[64:67], v[68:71], 0
	v_cvt_pk_bf16_f32 v158, v116, v117
	v_cvt_pk_bf16_f32 v159, v118, v119
	ds_read_b64_tr_b16 v[116:117], v168 offset:25600
	ds_read_b64_tr_b16 v[118:119], v168 offset:26112
	ds_read_b128 v[190:193], v188 offset:1024
	v_add_f32_e32 v144, v122, v144
	v_add_f32_e32 v144, v123, v144
	v_add_f32_e32 v144, v124, v144
	v_add_f32_e32 v144, v125, v144
	v_cvt_pk_bf16_f32 v152, v120, v121
	v_cvt_pk_bf16_f32 v153, v122, v123
	s_waitcnt lgkmcnt(0)
	v_mfma_f32_32x32x16_bf16 v[128:143], v[164:167], v[190:193], v[128:143]
	ds_read_b64_tr_b16 v[120:121], v168 offset:29696
	ds_read_b64_tr_b16 v[122:123], v168 offset:30208
	ds_read_b128 v[164:167], v188 offset:1024
	v_add_f32_e32 v144, v126, v144
	v_add_f32_e32 v144, v127, v144
	v_add_f32_e32 v144, v96, v144
	v_add_f32_e32 v144, v97, v144
	s_waitcnt lgkmcnt(0)
	v_mfma_f32_32x32x16_bf16 v[64:79], v[92:95], v[164:167], v[64:79]
	v_cvt_pk_bf16_f32 v154, v124, v125
	v_cvt_pk_bf16_f32 v155, v126, v127
	ds_read_b64_tr_b16 v[92:93], v168 offset:26624
	ds_read_b64_tr_b16 v[94:95], v168 offset:27136
	ds_read_b128 v[124:127], v188 offset:2048
	v_add_f32_e32 v144, v98, v144
	v_add_f32_e32 v144, v99, v144
	v_add_f32_e32 v144, v100, v144
	v_add_f32_e32 v144, v101, v144
	v_cvt_pk_bf16_f32 v148, v96, v97
	v_cvt_pk_bf16_f32 v149, v98, v99
	s_waitcnt lgkmcnt(0)
	v_mfma_f32_32x32x16_bf16 v[128:143], v[160:163], v[124:127], v[128:143]
	ds_read_b64_tr_b16 v[96:97], v168 offset:30720
	ds_read_b64_tr_b16 v[98:99], v168 offset:31232
	ds_read_b128 v[124:127], v188 offset:2048
	v_add_f32_e32 v144, v102, v144
	v_add_f32_e32 v144, v103, v144
	v_add_f32_e32 v144, v104, v144
	v_add_f32_e32 v144, v105, v144
	s_waitcnt lgkmcnt(0)
	v_mfma_f32_32x32x16_bf16 v[64:79], v[84:87], v[124:127], v[64:79]
	v_cvt_pk_bf16_f32 v150, v100, v101
	v_cvt_pk_bf16_f32 v151, v102, v103
	ds_read_b64_tr_b16 v[100:101], v168 offset:27648
	ds_read_b64_tr_b16 v[102:103], v168 offset:28160
	ds_read_b128 v[84:87], v188 offset:3072
	v_add_f32_e32 v124, v106, v144
	v_add_f32_e32 v124, v107, v124
	v_add_f32_e32 v124, v108, v124
	v_add_f32_e32 v124, v109, v124
	v_cvt_pk_bf16_f32 v144, v104, v105
	v_cvt_pk_bf16_f32 v145, v106, v107
	s_waitcnt lgkmcnt(0)
	v_mfma_f32_32x32x16_bf16 v[128:143], v[88:91], v[84:87], v[128:143]
	ds_read_b64_tr_b16 v[88:89], v168 offset:31744
	ds_read_b64_tr_b16 v[90:91], v168 offset:32256
	ds_read_b128 v[84:87], v188 offset:3072
	v_add_f32_e32 v104, v110, v124
	v_add_f32_e32 v104, v111, v104
	v_add_f32_e32 v104, 0, v104
	v_cvt_pk_bf16_f32 v146, v108, v109
	s_waitcnt lgkmcnt(0)
; #define WAIT_BAR(N) asm volatile("s_waitcnt vmcnt(" #N ") lgkmcnt(0)\n\ts_barrier":::"memory")
;   #define RESC() do{ if(!NOMAX&&resc){ asm volatile("s_waitcnt lgkmcnt(0)":::"memory"); \
;       _Pragma("unroll") for(int d_=0;d_<2*VM;++d_) _Pragma("unroll") for(int r=0;r<16;++r)o[d_][r]*=wsf[crow(r,hi)]; } }while(0)
;   #define ROT() do{sl_prev=sl_cur;sl_cur=sl_next;sl_next=(sl_next==(NSLOT-1)*SLOTB)?0:sl_next+SLOTB;}while(0)
;   #define ENDW(tt) do{ if((tt)+3<NT){ if constexpr(VM==2){WAIT_BAR(3);}else{WAIT_BAR(2);} } else if((tt)+2<NT){ if constexpr(VM==2){WAIT_BAR(2);}else{WAIT_BAR(1);} } else {WAIT_BAR(0);} }while(0)
; template<int THRL,int VM,bool NOMAX> __device__ __forceinline__ void attn_unit(const bf16*Qb,const bf16*__restrict__ Kh,const bf16*__restrict__ Vh,bf16*Ob,const int NT,const int sp,float*wscr,char*shm){
;     ...
;   int t=1;
;   for(;t+5<NT;t+=2){
;     STEP(pB0,pB1,pA0,pA1,t,true,true,true);     if constexpr(VM==2){WAIT_BAR(3);}else{WAIT_BAR(2);} RESC(); ROT();
;     STEP(pA0,pA1,pB0,pB1,t+1,true,true,true);   if constexpr(VM==2){WAIT_BAR(3);}else{WAIT_BAR(2);} RESC(); ROT();
;   }
;     ...
;   for(;t+1<NT;t+=2){
;     STEP(pB0,pB1,pA0,pA1,t,(t+3<NT),(t+1<NT),(t+1<NT));       ENDW(t);   RESC(); ROT();
;     STEP(pA0,pA1,pB0,pB1,t+1,(t+4<NT),(t+2<NT),(t+2<NT));     ENDW(t+1); RESC(); ROT();
	v_mfma_f32_32x32x16_bf16 v[64:79], v[80:83], v[84:87], v[64:79]
	v_cvt_pk_bf16_f32 v147, v110, v111
	v_lshl_add_u64 v[80:81], v[174:175], 0, s[62:63]
	s_add_i32 s86, s85, 0x2000
	s_mov_b32 s87, m0
	s_mov_b32 m0, s86
	s_nop 0
	global_load_lds_dwordx4 v[80:81], off
	s_mov_b32 m0, s87
	v_lshl_add_u64 v[80:81], v[170:171], 0, s[64:65]
	s_add_i32 s86, s85, 0xe000
	s_mov_b32 s87, m0
	s_mov_b32 m0, s86
	s_nop 0
	global_load_lds_dwordx4 v[80:81], off
	s_mov_b32 m0, s87
	v_lshl_add_u64 v[80:81], v[172:173], 0, s[64:65]
	s_add_i32 s85, s85, 0x10000
	s_mov_b32 s86, m0
	s_mov_b32 m0, s85
	s_nop 0
	global_load_lds_dwordx4 v[80:81], off
	s_mov_b32 m0, s86
	v_add_f32_e32 v198, v198, v104
	v_mfma_f32_32x32x16_bf16 v[48:63], v[156:159], v[178:181], v[48:63]
	ds_read_b64_tr_b16 v[104:105], v168 offset:32768
	ds_read_b64_tr_b16 v[106:107], v168 offset:33280
	v_exp_f32_e32 v128, v128
	v_exp_f32_e32 v129, v129
	v_mfma_f32_32x32x16_bf16 v[32:47], v[156:159], v[112:115], v[32:47]
	ds_read_b64_tr_b16 v[108:109], v168 offset:36864
	ds_read_b64_tr_b16 v[110:111], v168 offset:37376
	v_exp_f32_e32 v130, v130
	v_exp_f32_e32 v131, v131
	ds_read_b128 v[84:87], v189 offset:16384
	ds_read_b128 v[80:83], v189 offset:16896
	v_mfma_f32_32x32x16_bf16 v[48:63], v[152:155], v[116:119], v[48:63]
	ds_read_b64_tr_b16 v[178:179], v168 offset:33792
	ds_read_b64_tr_b16 v[180:181], v168 offset:34304
	v_exp_f32_e32 v132, v132
	v_exp_f32_e32 v133, v133
	ds_read_b128 v[164:167], v189 offset:18432
	ds_read_b128 v[124:127], v189 offset:18944
	v_mfma_f32_32x32x16_bf16 v[32:47], v[152:155], v[120:123], v[32:47]
	ds_read_b64_tr_b16 v[190:191], v168 offset:37888
	ds_read_b64_tr_b16 v[192:193], v168 offset:38400
	v_exp_f32_e32 v134, v134
	v_exp_f32_e32 v135, v135
	ds_read_b128 v[160:163], v189 offset:20480
	ds_read_b128 v[116:119], v189 offset:20992
	v_mfma_f32_32x32x16_bf16 v[48:63], v[148:151], v[92:95], v[48:63]
	ds_read_b64_tr_b16 v[194:195], v168 offset:34816
	ds_read_b64_tr_b16 v[196:197], v168 offset:35328
	v_exp_f32_e32 v136, v136
	v_exp_f32_e32 v137, v137
	ds_read_b128 v[120:123], v189 offset:22528
	ds_read_b128 v[112:115], v189 offset:23040
	v_mfma_f32_32x32x16_bf16 v[32:47], v[148:151], v[96:99], v[32:47]
	ds_read_b64_tr_b16 v[92:93], v168 offset:38912
	ds_read_b64_tr_b16 v[94:95], v168 offset:39424
	v_exp_f32_e32 v138, v138
	v_exp_f32_e32 v139, v139
	v_mfma_f32_32x32x16_bf16 v[48:63], v[144:147], v[100:103], v[48:63]
	ds_read_b64_tr_b16 v[96:97], v168 offset:35840
	ds_read_b64_tr_b16 v[98:99], v168 offset:36352
	v_exp_f32_e32 v140, v140
	v_exp_f32_e32 v141, v141
	v_mfma_f32_32x32x16_bf16 v[32:47], v[144:147], v[88:91], v[32:47]
	ds_read_b64_tr_b16 v[100:101], v168 offset:39936
	ds_read_b64_tr_b16 v[102:103], v168 offset:40448
	v_exp_f32_e32 v142, v142
	v_exp_f32_e32 v143, v143
	s_waitcnt lgkmcnt(14)
	v_mfma_f32_32x32x16_bf16 v[16:31], v[156:159], v[104:107], v[16:31]
	v_exp_f32_e32 v64, v64
	v_exp_f32_e32 v65, v65
	v_mfma_f32_32x32x16_bf16 v[0:15], v[156:159], v[108:111], v[0:15]
	v_exp_f32_e32 v66, v66
	v_exp_f32_e32 v67, v67
	v_mfma_f32_32x32x16_bf16 v[16:31], v[152:155], v[178:181], v[16:31]
	v_exp_f32_e32 v68, v68
	v_exp_f32_e32 v69, v69
	s_waitcnt lgkmcnt(12)
	v_mfma_f32_32x32x16_bf16 v[0:15], v[152:155], v[190:193], v[0:15]
	v_exp_f32_e32 v70, v70
	v_exp_f32_e32 v71, v71
	s_waitcnt lgkmcnt(8)
	v_mfma_f32_32x32x16_bf16 v[16:31], v[148:151], v[194:197], v[16:31]
	v_exp_f32_e32 v72, v72
	v_exp_f32_e32 v73, v73
	s_waitcnt lgkmcnt(4)
	v_mfma_f32_32x32x16_bf16 v[0:15], v[148:151], v[92:95], v[0:15]
	v_exp_f32_e32 v74, v74
	v_exp_f32_e32 v75, v75
	s_waitcnt lgkmcnt(2)
	v_mfma_f32_32x32x16_bf16 v[16:31], v[144:147], v[96:99], v[16:31]
	v_exp_f32_e32 v76, v76
	v_exp_f32_e32 v77, v77
	s_waitcnt lgkmcnt(0)
	v_mfma_f32_32x32x16_bf16 v[0:15], v[144:147], v[100:103], v[0:15]
	v_exp_f32_e32 v78, v78
	v_exp_f32_e32 v79, v79
	s_waitcnt vmcnt(3) lgkmcnt(0)
	s_barrier
	ds_read_b64_tr_b16 v[178:179], v168 offset:40960
	ds_read_b64_tr_b16 v[180:181], v168 offset:41472
	v_add_f32_e32 v92, v128, v129
	ds_read_b128 v[88:91], v188
	v_add_f32_e32 v92, v130, v92
	v_add_f32_e32 v92, v131, v92
	v_add_f32_e32 v92, v132, v92
	v_add_f32_e32 v92, v133, v92
	v_cvt_pk_bf16_f32 v156, v128, v129
	v_cvt_pk_bf16_f32 v157, v130, v131
	s_waitcnt lgkmcnt(0)
	v_mfma_f32_32x32x16_bf16 v[96:111], v[84:87], v[88:91], 0
	ds_read_b64_tr_b16 v[128:129], v168 offset:45056
	ds_read_b64_tr_b16 v[130:131], v168 offset:45568
	ds_read_b128 v[84:87], v188
	v_add_f32_e32 v88, v134, v92
	v_add_f32_e32 v88, v135, v88
	v_add_f32_e32 v88, v136, v88
	v_add_f32_e32 v144, v137, v88
	v_cvt_pk_bf16_f32 v158, v132, v133
	v_cvt_pk_bf16_f32 v159, v134, v135
	s_waitcnt lgkmcnt(0)
	v_mfma_f32_32x32x16_bf16 v[80:95], v[80:83], v[84:87], 0
	ds_read_b64_tr_b16 v[132:133], v168 offset:41984
	ds_read_b64_tr_b16 v[134:135], v168 offset:42496
	ds_read_b128 v[190:193], v188 offset:1024
	v_add_f32_e32 v144, v138, v144
	v_add_f32_e32 v144, v139, v144
	v_add_f32_e32 v144, v140, v144
	v_add_f32_e32 v144, v141, v144
	v_cvt_pk_bf16_f32 v152, v136, v137
	v_cvt_pk_bf16_f32 v153, v138, v139
	s_waitcnt lgkmcnt(0)
	v_mfma_f32_32x32x16_bf16 v[96:111], v[164:167], v[190:193], v[96:111]
	ds_read_b64_tr_b16 v[136:137], v168 offset:46080
	ds_read_b64_tr_b16 v[138:139], v168 offset:46592
	ds_read_b128 v[164:167], v188 offset:1024
	v_add_f32_e32 v144, v142, v144
	v_add_f32_e32 v144, v143, v144
	v_add_f32_e32 v144, v64, v144
	v_add_f32_e32 v144, v65, v144
	v_cvt_pk_bf16_f32 v154, v140, v141
	v_cvt_pk_bf16_f32 v155, v142, v143
	s_waitcnt lgkmcnt(0)
; #define WAIT_BAR(N) asm volatile("s_waitcnt vmcnt(" #N ") lgkmcnt(0)\n\ts_barrier":::"memory")
;   #define RESC() do{ if(!NOMAX&&resc){ asm volatile("s_waitcnt lgkmcnt(0)":::"memory"); \
;       _Pragma("unroll") for(int d_=0;d_<2*VM;++d_) _Pragma("unroll") for(int r=0;r<16;++r)o[d_][r]*=wsf[crow(r,hi)]; } }while(0)
;   #define ROT() do{sl_prev=sl_cur;sl_cur=sl_next;sl_next=(sl_next==(NSLOT-1)*SLOTB)?0:sl_next+SLOTB;}while(0)
;   #define ENDW(tt) do{ if((tt)+3<NT){ if constexpr(VM==2){WAIT_BAR(3);}else{WAIT_BAR(2);} } else if((tt)+2<NT){ if constexpr(VM==2){WAIT_BAR(2);}else{WAIT_BAR(1);} } else {WAIT_BAR(0);} }while(0)
; template<int THRL,int VM,bool NOMAX> __device__ __forceinline__ void attn_unit(const bf16*Qb,const bf16*__restrict__ Kh,const bf16*__restrict__ Vh,bf16*Ob,const int NT,const int sp,float*wscr,char*shm){
;     ...
;   int t=1;
;   for(;t+5<NT;t+=2){
;     STEP(pB0,pB1,pA0,pA1,t,true,true,true);     if constexpr(VM==2){WAIT_BAR(3);}else{WAIT_BAR(2);} RESC(); ROT();
;     STEP(pA0,pA1,pB0,pB1,t+1,true,true,true);   if constexpr(VM==2){WAIT_BAR(3);}else{WAIT_BAR(2);} RESC(); ROT();
;   }
;     ...
;   for(;t+1<NT;t+=2){
;     STEP(pB0,pB1,pA0,pA1,t,(t+3<NT),(t+1<NT),(t+1<NT));       ENDW(t);   RESC(); ROT();
;     STEP(pA0,pA1,pB0,pB1,t+1,(t+4<NT),(t+2<NT),(t+2<NT));     ENDW(t+1); RESC(); ROT();
	v_mfma_f32_32x32x16_bf16 v[80:95], v[124:127], v[164:167], v[80:95]
	ds_read_b64_tr_b16 v[124:125], v168 offset:43008
	ds_read_b64_tr_b16 v[126:127], v168 offset:43520
	ds_read_b128 v[140:143], v188 offset:2048
	v_add_f32_e32 v144, v66, v144
	v_add_f32_e32 v144, v67, v144
	v_add_f32_e32 v144, v68, v144
	v_add_f32_e32 v144, v69, v144
	v_cvt_pk_bf16_f32 v148, v64, v65
	v_cvt_pk_bf16_f32 v149, v66, v67
	s_waitcnt lgkmcnt(0)
	v_mfma_f32_32x32x16_bf16 v[96:111], v[160:163], v[140:143], v[96:111]
	ds_read_b64_tr_b16 v[190:191], v168 offset:47104
	ds_read_b64_tr_b16 v[192:193], v168 offset:47616
	ds_read_b128 v[64:67], v188 offset:2048
	v_add_f32_e32 v140, v70, v144
	v_add_f32_e32 v140, v71, v140
	v_add_f32_e32 v140, v72, v140
	v_add_f32_e32 v140, v73, v140
	v_cvt_pk_bf16_f32 v150, v68, v69
	v_cvt_pk_bf16_f32 v151, v70, v71
	s_waitcnt lgkmcnt(0)
	v_mfma_f32_32x32x16_bf16 v[80:95], v[116:119], v[64:67], v[80:95]
	ds_read_b64_tr_b16 v[116:117], v168 offset:44032
	ds_read_b64_tr_b16 v[118:119], v168 offset:44544
	ds_read_b128 v[64:67], v188 offset:3072
	v_add_f32_e32 v68, v74, v140
	v_add_f32_e32 v68, v75, v68
	v_add_f32_e32 v68, v76, v68
	v_add_f32_e32 v68, v77, v68
	v_cvt_pk_bf16_f32 v144, v72, v73
	v_cvt_pk_bf16_f32 v145, v74, v75
	s_waitcnt lgkmcnt(0)
	v_mfma_f32_32x32x16_bf16 v[96:111], v[120:123], v[64:67], v[96:111]
	ds_read_b64_tr_b16 v[72:73], v168 offset:48128
	ds_read_b64_tr_b16 v[74:75], v168 offset:48640
	ds_read_b128 v[64:67], v188 offset:3072
	v_add_f32_e32 v68, v78, v68
	v_add_f32_e32 v68, v79, v68
	v_add_f32_e32 v68, 0, v68
	v_cvt_pk_bf16_f32 v146, v76, v77
	v_cvt_pk_bf16_f32 v147, v78, v79
	s_waitcnt lgkmcnt(0)
	v_mfma_f32_32x32x16_bf16 v[80:95], v[112:115], v[64:67], v[80:95]
	v_lshl_add_u64 v[64:65], v[170:171], 0, s[58:59]
	s_mov_b32 s85, m0
	s_mov_b32 m0, s16
	s_nop 0
	global_load_lds_dwordx4 v[64:65], off
	s_mov_b32 m0, s85
	v_lshl_add_u64 v[64:65], v[172:173], 0, s[58:59]
	s_addk_i32 s16, 0x2000
	s_mov_b32 s85, m0
	s_mov_b32 m0, s16
	s_nop 0
	global_load_lds_dwordx4 v[64:65], off
	s_mov_b32 m0, s85
	v_add_f32_e32 v174, v198, v68
	v_mfma_f32_32x32x16_bf16 v[48:63], v[156:159], v[178:181], v[48:63]
	ds_read_b64_tr_b16 v[76:77], v168 offset:49152
	ds_read_b64_tr_b16 v[78:79], v168 offset:49664
	v_exp_f32_e32 v96, v96
	v_exp_f32_e32 v97, v97
	v_mfma_f32_32x32x16_bf16 v[32:47], v[156:159], v[128:131], v[32:47]
	ds_read_b64_tr_b16 v[112:113], v168 offset:53248
	ds_read_b64_tr_b16 v[114:115], v168 offset:53760
	v_exp_f32_e32 v98, v98
	v_exp_f32_e32 v99, v99
	ds_read_b128 v[68:71], v189
	ds_read_b128 v[64:67], v189 offset:512
	v_mfma_f32_32x32x16_bf16 v[48:63], v[152:155], v[132:135], v[48:63]
	ds_read_b64_tr_b16 v[120:121], v168 offset:50176
	ds_read_b64_tr_b16 v[122:123], v168 offset:50688
	v_exp_f32_e32 v100, v100
	v_exp_f32_e32 v101, v101
	ds_read_b128 v[164:167], v189 offset:2048
	ds_read_b128 v[140:143], v189 offset:2560
	v_mfma_f32_32x32x16_bf16 v[32:47], v[152:155], v[136:139], v[32:47]
	ds_read_b64_tr_b16 v[178:179], v168 offset:54272
	ds_read_b64_tr_b16 v[180:181], v168 offset:54784
	v_exp_f32_e32 v102, v102
	v_exp_f32_e32 v103, v103
	ds_read_b128 v[160:163], v189 offset:4096
	ds_read_b128 v[132:135], v189 offset:4608
	v_mfma_f32_32x32x16_bf16 v[48:63], v[148:151], v[124:127], v[48:63]
	ds_read_b64_tr_b16 v[194:195], v168 offset:51200
	ds_read_b64_tr_b16 v[196:197], v168 offset:51712
	v_exp_f32_e32 v104, v104
	v_exp_f32_e32 v105, v105
	ds_read_b128 v[136:139], v189 offset:6144
	ds_read_b128 v[128:131], v189 offset:6656
	v_mfma_f32_32x32x16_bf16 v[32:47], v[148:151], v[190:193], v[32:47]
	ds_read_b64_tr_b16 v[124:125], v168 offset:55296
	ds_read_b64_tr_b16 v[126:127], v168 offset:55808
	v_exp_f32_e32 v106, v106
	v_exp_f32_e32 v107, v107
	v_mfma_f32_32x32x16_bf16 v[48:63], v[144:147], v[116:119], v[48:63]
	ds_read_b64_tr_b16 v[190:191], v168 offset:52224
	ds_read_b64_tr_b16 v[192:193], v168 offset:52736
	v_exp_f32_e32 v108, v108
	v_exp_f32_e32 v109, v109
	v_mfma_f32_32x32x16_bf16 v[32:47], v[144:147], v[72:75], v[32:47]
	ds_read_b64_tr_b16 v[116:117], v168 offset:56320
	ds_read_b64_tr_b16 v[118:119], v168 offset:56832
	v_exp_f32_e32 v110, v110
	v_exp_f32_e32 v111, v111
	s_waitcnt lgkmcnt(14)
	v_mfma_f32_32x32x16_bf16 v[16:31], v[156:159], v[76:79], v[16:31]
	v_exp_f32_e32 v80, v80
	v_exp_f32_e32 v81, v81
	v_mfma_f32_32x32x16_bf16 v[0:15], v[156:159], v[112:115], v[0:15]
	v_exp_f32_e32 v82, v82
	v_exp_f32_e32 v83, v83
	v_mfma_f32_32x32x16_bf16 v[16:31], v[152:155], v[120:123], v[16:31]
	v_exp_f32_e32 v84, v84
	v_exp_f32_e32 v85, v85
	s_waitcnt lgkmcnt(12)
	v_mfma_f32_32x32x16_bf16 v[0:15], v[152:155], v[178:181], v[0:15]
	v_exp_f32_e32 v86, v86
	v_exp_f32_e32 v87, v87
	s_waitcnt lgkmcnt(8)
	v_mfma_f32_32x32x16_bf16 v[16:31], v[148:151], v[194:197], v[16:31]
	v_exp_f32_e32 v88, v88
	v_exp_f32_e32 v89, v89
	s_waitcnt lgkmcnt(4)
	v_mfma_f32_32x32x16_bf16 v[0:15], v[148:151], v[124:127], v[0:15]
	v_exp_f32_e32 v90, v90
	v_exp_f32_e32 v91, v91
	s_waitcnt lgkmcnt(2)
	v_mfma_f32_32x32x16_bf16 v[16:31], v[144:147], v[190:193], v[16:31]
	v_exp_f32_e32 v92, v92
	v_exp_f32_e32 v93, v93
	s_waitcnt lgkmcnt(0)
	v_mfma_f32_32x32x16_bf16 v[0:15], v[144:147], v[116:119], v[0:15]
	v_exp_f32_e32 v94, v94
	v_exp_f32_e32 v95, v95
	s_waitcnt vmcnt(2) lgkmcnt(0)
	s_barrier
; #define WAIT_BAR(N) asm volatile("s_waitcnt vmcnt(" #N ") lgkmcnt(0)\n\ts_barrier":::"memory")
;   #define RESC() do{ if(!NOMAX&&resc){ asm volatile("s_waitcnt lgkmcnt(0)":::"memory"); \
;       _Pragma("unroll") for(int d_=0;d_<2*VM;++d_) _Pragma("unroll") for(int r=0;r<16;++r)o[d_][r]*=wsf[crow(r,hi)]; } }while(0)
;   #define ROT() do{sl_prev=sl_cur;sl_cur=sl_next;sl_next=(sl_next==(NSLOT-1)*SLOTB)?0:sl_next+SLOTB;}while(0)
;   #define ENDW(tt) do{ if((tt)+3<NT){ if constexpr(VM==2){WAIT_BAR(3);}else{WAIT_BAR(2);} } else if((tt)+2<NT){ if constexpr(VM==2){WAIT_BAR(2);}else{WAIT_BAR(1);} } else {WAIT_BAR(0);} }while(0)
; template<int THRL,int VM,bool NOMAX> __device__ __forceinline__ void attn_unit(const bf16*Qb,const bf16*__restrict__ Kh,const bf16*__restrict__ Vh,bf16*Ob,const int NT,const int sp,float*wscr,char*shm){
;     ...
;   int t=1;
;   for(;t+5<NT;t+=2){
;     STEP(pB0,pB1,pA0,pA1,t,true,true,true);     if constexpr(VM==2){WAIT_BAR(3);}else{WAIT_BAR(2);} RESC(); ROT();
;     STEP(pA0,pA1,pB0,pB1,t+1,true,true,true);   if constexpr(VM==2){WAIT_BAR(3);}else{WAIT_BAR(2);} RESC(); ROT();
;   }
;     ...
;   for(;t+1<NT;t+=2){
;     STEP(pB0,pB1,pA0,pA1,t,(t+3<NT),(t+1<NT),(t+1<NT));       ENDW(t);   RESC(); ROT();
;     STEP(pA0,pA1,pB0,pB1,t+1,(t+4<NT),(t+2<NT),(t+2<NT));     ENDW(t+1); RESC(); ROT();
	ds_read_b64_tr_b16 v[178:179], v168 offset:57344
	ds_read_b64_tr_b16 v[180:181], v168 offset:57856
	v_add_f32_e32 v76, v96, v97
	ds_read_b128 v[72:75], v188
	v_add_f32_e32 v76, v98, v76
	v_add_f32_e32 v76, v99, v76
	v_add_f32_e32 v76, v100, v76
	v_add_f32_e32 v76, v101, v76
	v_cvt_pk_bf16_f32 v156, v96, v97
	v_cvt_pk_bf16_f32 v157, v98, v99
	s_waitcnt lgkmcnt(0)
	v_mfma_f32_32x32x16_bf16 v[112:127], v[68:71], v[72:75], 0
	ds_read_b64_tr_b16 v[96:97], v168 offset:61440
	ds_read_b64_tr_b16 v[98:99], v168 offset:61952
	ds_read_b128 v[68:71], v188
	v_add_f32_e32 v72, v102, v76
	v_add_f32_e32 v72, v103, v72
	v_add_f32_e32 v72, v104, v72
	v_add_f32_e32 v144, v105, v72
	s_waitcnt lgkmcnt(0)
	v_mfma_f32_32x32x16_bf16 v[64:79], v[64:67], v[68:71], 0
	v_cvt_pk_bf16_f32 v158, v100, v101
	v_cvt_pk_bf16_f32 v159, v102, v103
	ds_read_b64_tr_b16 v[100:101], v168 offset:58368
	ds_read_b64_tr_b16 v[102:103], v168 offset:58880
	ds_read_b128 v[190:193], v188 offset:1024
	v_add_f32_e32 v144, v106, v144
	v_add_f32_e32 v144, v107, v144
	v_add_f32_e32 v144, v108, v144
	v_add_f32_e32 v144, v109, v144
	v_cvt_pk_bf16_f32 v152, v104, v105
	v_cvt_pk_bf16_f32 v153, v106, v107
	s_waitcnt lgkmcnt(0)
	v_mfma_f32_32x32x16_bf16 v[112:127], v[164:167], v[190:193], v[112:127]
	ds_read_b64_tr_b16 v[104:105], v168 offset:62464
	ds_read_b64_tr_b16 v[106:107], v168 offset:62976
	ds_read_b128 v[164:167], v188 offset:1024
	v_add_f32_e32 v144, v110, v144
	v_add_f32_e32 v144, v111, v144
	v_add_f32_e32 v144, v80, v144
	v_add_f32_e32 v144, v81, v144
	s_waitcnt lgkmcnt(0)
	v_mfma_f32_32x32x16_bf16 v[64:79], v[140:143], v[164:167], v[64:79]
	v_cvt_pk_bf16_f32 v154, v108, v109
	v_cvt_pk_bf16_f32 v155, v110, v111
	ds_read_b64_tr_b16 v[108:109], v168 offset:59392
	ds_read_b64_tr_b16 v[110:111], v168 offset:59904
	ds_read_b128 v[140:143], v188 offset:2048
	v_add_f32_e32 v144, v82, v144
	v_add_f32_e32 v144, v83, v144
	v_add_f32_e32 v144, v84, v144
	v_add_f32_e32 v144, v85, v144
	v_cvt_pk_bf16_f32 v148, v80, v81
	v_cvt_pk_bf16_f32 v149, v82, v83
	s_waitcnt lgkmcnt(0)
	v_mfma_f32_32x32x16_bf16 v[112:127], v[160:163], v[140:143], v[112:127]
	ds_read_b64_tr_b16 v[190:191], v168 offset:63488
	ds_read_b64_tr_b16 v[192:193], v168 offset:64000
	ds_read_b128 v[80:83], v188 offset:2048
	v_add_f32_e32 v140, v86, v144
	v_add_f32_e32 v140, v87, v140
	v_add_f32_e32 v140, v88, v140
	v_add_f32_e32 v140, v89, v140
	s_waitcnt lgkmcnt(0)
	v_mfma_f32_32x32x16_bf16 v[64:79], v[132:135], v[80:83], v[64:79]
	v_cvt_pk_bf16_f32 v150, v84, v85
	v_cvt_pk_bf16_f32 v151, v86, v87
	ds_read_b64_tr_b16 v[84:85], v168 offset:60416
	ds_read_b64_tr_b16 v[86:87], v168 offset:60928
	ds_read_b128 v[80:83], v188 offset:3072
	v_add_f32_e32 v132, v90, v140
	v_add_f32_e32 v132, v91, v132
	v_add_f32_e32 v132, v92, v132
	v_add_f32_e32 v132, v93, v132
	v_cvt_pk_bf16_f32 v144, v88, v89
	v_cvt_pk_bf16_f32 v145, v90, v91
	s_waitcnt lgkmcnt(0)
	v_mfma_f32_32x32x16_bf16 v[112:127], v[136:139], v[80:83], v[112:127]
	ds_read_b64_tr_b16 v[88:89], v168 offset:64512
	ds_read_b64_tr_b16 v[90:91], v168 offset:65024
	ds_read_b128 v[80:83], v188 offset:3072
	v_add_f32_e32 v132, v94, v132
	v_add_f32_e32 v132, v95, v132
	v_add_f32_e32 v132, 0, v132
	v_cvt_pk_bf16_f32 v146, v92, v93
	s_waitcnt lgkmcnt(0)
	v_mfma_f32_32x32x16_bf16 v[64:79], v[128:131], v[80:83], v[64:79]
	v_cvt_pk_bf16_f32 v147, v94, v95
	v_lshl_add_u64 v[80:81], v[170:171], 0, s[62:63]
	s_mov_b32 s16, m0
	s_mov_b32 m0, s17
	s_nop 0
	global_load_lds_dwordx4 v[80:81], off
	s_mov_b32 m0, s16
	v_lshl_add_u64 v[80:81], v[172:173], 0, s[62:63]
	s_mov_b32 s16, m0
	s_mov_b32 m0, s35
	s_nop 0
	global_load_lds_dwordx4 v[80:81], off
	s_mov_b32 m0, s16
	v_add_f32_e32 v174, v174, v132
	v_mfma_f32_32x32x16_bf16 v[48:63], v[156:159], v[178:181], v[48:63]
	ds_read_b64_tr_b16 v[92:93], v177 offset:40960
	ds_read_b64_tr_b16 v[94:95], v177 offset:41472
	v_exp_f32_e32 v112, v112
	v_exp_f32_e32 v113, v113
	v_mfma_f32_32x32x16_bf16 v[32:47], v[156:159], v[96:99], v[32:47]
	ds_read_b64_tr_b16 v[170:171], v177 offset:45056
	ds_read_b64_tr_b16 v[172:173], v177 offset:45568
	v_exp_f32_e32 v114, v114
	v_exp_f32_e32 v115, v115
	ds_read_b128 v[80:83], v189 offset:8192
	ds_read_b128 v[96:99], v189 offset:8704
	v_mfma_f32_32x32x16_bf16 v[48:63], v[152:155], v[100:103], v[48:63]
	ds_read_b64_tr_b16 v[178:179], v177 offset:41984
	ds_read_b64_tr_b16 v[180:181], v177 offset:42496
	v_exp_f32_e32 v116, v116
	v_exp_f32_e32 v117, v117
	ds_read_b128 v[164:167], v189 offset:10240
	ds_read_b128 v[140:143], v189 offset:10752
	v_mfma_f32_32x32x16_bf16 v[32:47], v[152:155], v[104:107], v[32:47]
	ds_read_b64_tr_b16 v[100:101], v177 offset:46080
	ds_read_b64_tr_b16 v[102:103], v177 offset:46592
	v_exp_f32_e32 v118, v118
	v_exp_f32_e32 v119, v119
	ds_read_b128 v[160:163], v189 offset:12288
	ds_read_b128 v[132:135], v189 offset:12800
	v_mfma_f32_32x32x16_bf16 v[48:63], v[148:151], v[108:111], v[48:63]
	ds_read_b64_tr_b16 v[104:105], v177 offset:43008
	ds_read_b64_tr_b16 v[106:107], v177 offset:43520
	v_exp_f32_e32 v120, v120
	v_exp_f32_e32 v121, v121
	ds_read_b128 v[136:139], v189 offset:14336
	ds_read_b128 v[128:131], v189 offset:14848
	v_mfma_f32_32x32x16_bf16 v[32:47], v[148:151], v[190:193], v[32:47]
	ds_read_b64_tr_b16 v[108:109], v177 offset:47104
	ds_read_b64_tr_b16 v[110:111], v177 offset:47616
	v_exp_f32_e32 v122, v122
	v_exp_f32_e32 v123, v123
	v_mfma_f32_32x32x16_bf16 v[48:63], v[144:147], v[84:87], v[48:63]
	ds_read_b64_tr_b16 v[190:191], v177 offset:44032
	ds_read_b64_tr_b16 v[192:193], v177 offset:44544
	v_exp_f32_e32 v124, v124
	v_exp_f32_e32 v125, v125
	v_mfma_f32_32x32x16_bf16 v[32:47], v[144:147], v[88:91], v[32:47]
	ds_read_b64_tr_b16 v[84:85], v177 offset:48128
	ds_read_b64_tr_b16 v[86:87], v177 offset:48640
	v_exp_f32_e32 v126, v126
	v_exp_f32_e32 v127, v127
	s_waitcnt lgkmcnt(14)
	v_mfma_f32_32x32x16_bf16 v[16:31], v[156:159], v[92:95], v[16:31]
	v_exp_f32_e32 v64, v64
	v_exp_f32_e32 v65, v65
	v_mfma_f32_32x32x16_bf16 v[0:15], v[156:159], v[170:173], v[0:15]
	v_exp_f32_e32 v66, v66
	v_exp_f32_e32 v67, v67
	v_mfma_f32_32x32x16_bf16 v[16:31], v[152:155], v[178:181], v[16:31]
	v_exp_f32_e32 v68, v68
	v_exp_f32_e32 v69, v69
	s_waitcnt lgkmcnt(12)
	v_mfma_f32_32x32x16_bf16 v[0:15], v[152:155], v[100:103], v[0:15]
	v_exp_f32_e32 v70, v70
	v_exp_f32_e32 v71, v71
	s_waitcnt lgkmcnt(8)
	v_mfma_f32_32x32x16_bf16 v[16:31], v[148:151], v[104:107], v[16:31]
	v_exp_f32_e32 v72, v72
	v_exp_f32_e32 v73, v73
	s_waitcnt lgkmcnt(4)
	v_mfma_f32_32x32x16_bf16 v[0:15], v[148:151], v[108:111], v[0:15]
	v_exp_f32_e32 v74, v74
	v_exp_f32_e32 v75, v75
	s_waitcnt lgkmcnt(2)
	v_mfma_f32_32x32x16_bf16 v[16:31], v[144:147], v[190:193], v[16:31]
	v_exp_f32_e32 v76, v76
	v_exp_f32_e32 v77, v77
	s_waitcnt lgkmcnt(0)
	v_mfma_f32_32x32x16_bf16 v[0:15], v[144:147], v[84:87], v[0:15]
	v_exp_f32_e32 v78, v78
	v_exp_f32_e32 v79, v79
	s_waitcnt vmcnt(0) lgkmcnt(0)
	s_barrier
	ds_read_b64_tr_b16 v[170:171], v168 offset:24576
	ds_read_b64_tr_b16 v[172:173], v168 offset:25088
	v_add_f32_e32 v88, v112, v113
	ds_read_b128 v[84:87], v188
	v_add_f32_e32 v88, v114, v88
	v_add_f32_e32 v88, v115, v88
	v_add_f32_e32 v88, v116, v88
	v_add_f32_e32 v104, v117, v88
	v_cvt_pk_bf16_f32 v156, v112, v113
	v_cvt_pk_bf16_f32 v157, v114, v115
	s_waitcnt lgkmcnt(0)
	v_mfma_f32_32x32x16_bf16 v[80:95], v[80:83], v[84:87], 0
	ds_read_b64_tr_b16 v[112:113], v168 offset:28672
	ds_read_b64_tr_b16 v[114:115], v168 offset:29184
	ds_read_b128 v[100:103], v188
	v_add_f32_e32 v104, v118, v104
	v_add_f32_e32 v104, v119, v104
	v_add_f32_e32 v104, v120, v104
	v_add_f32_e32 v144, v121, v104
	v_cvt_pk_bf16_f32 v158, v116, v117
	v_cvt_pk_bf16_f32 v159, v118, v119
	s_waitcnt lgkmcnt(0)
	v_mfma_f32_32x32x16_bf16 v[96:111], v[96:99], v[100:103], 0
	ds_read_b64_tr_b16 v[116:117], v168 offset:25600
	ds_read_b64_tr_b16 v[118:119], v168 offset:26112
	ds_read_b128 v[178:181], v188 offset:1024
	v_add_f32_e32 v144, v122, v144
	v_add_f32_e32 v144, v123, v144
	v_add_f32_e32 v144, v124, v144
	v_add_f32_e32 v144, v125, v144
	v_cvt_pk_bf16_f32 v152, v120, v121
	v_cvt_pk_bf16_f32 v153, v122, v123
	s_waitcnt lgkmcnt(0)
	v_mfma_f32_32x32x16_bf16 v[80:95], v[164:167], v[178:181], v[80:95]
	ds_read_b64_tr_b16 v[120:121], v168 offset:29696
	ds_read_b64_tr_b16 v[122:123], v168 offset:30208
	ds_read_b128 v[164:167], v188 offset:1024
	v_add_f32_e32 v144, v126, v144
	v_add_f32_e32 v144, v127, v144
	v_add_f32_e32 v144, v64, v144
	v_add_f32_e32 v144, v65, v144
	v_cvt_pk_bf16_f32 v154, v124, v125
	v_cvt_pk_bf16_f32 v155, v126, v127
	s_waitcnt lgkmcnt(0)
	v_mfma_f32_32x32x16_bf16 v[96:111], v[140:143], v[164:167], v[96:111]
	ds_read_b64_tr_b16 v[124:125], v168 offset:26624
	ds_read_b64_tr_b16 v[126:127], v168 offset:27136
	ds_read_b128 v[140:143], v188 offset:2048
	v_add_f32_e32 v144, v66, v144
	v_add_f32_e32 v144, v67, v144
	v_add_f32_e32 v144, v68, v144
	v_add_f32_e32 v144, v69, v144
	v_cvt_pk_bf16_f32 v148, v64, v65
	v_cvt_pk_bf16_f32 v149, v66, v67
	s_waitcnt lgkmcnt(0)
	v_mfma_f32_32x32x16_bf16 v[80:95], v[160:163], v[140:143], v[80:95]
	ds_read_b64_tr_b16 v[64:65], v168 offset:30720
	ds_read_b64_tr_b16 v[66:67], v168 offset:31232
	ds_read_b128 v[140:143], v188 offset:2048
	v_add_f32_e32 v144, v70, v144
	v_add_f32_e32 v144, v71, v144
	v_add_f32_e32 v144, v72, v144
	v_add_f32_e32 v144, v73, v144
	v_cvt_pk_bf16_f32 v150, v68, v69
	v_cvt_pk_bf16_f32 v151, v70, v71
	s_waitcnt lgkmcnt(0)
	v_mfma_f32_32x32x16_bf16 v[96:111], v[132:135], v[140:143], v[96:111]
	ds_read_b64_tr_b16 v[68:69], v168 offset:27648
	ds_read_b64_tr_b16 v[70:71], v168 offset:28160
	ds_read_b128 v[132:135], v188 offset:3072
	v_add_f32_e32 v140, v74, v144
	v_add_f32_e32 v140, v75, v140
	v_add_f32_e32 v140, v76, v140
	v_add_f32_e32 v140, v77, v140
	v_cvt_pk_bf16_f32 v144, v72, v73
	v_cvt_pk_bf16_f32 v145, v74, v75
	s_waitcnt lgkmcnt(0)
	v_mfma_f32_32x32x16_bf16 v[80:95], v[136:139], v[132:135], v[80:95]
	ds_read_b64_tr_b16 v[72:73], v168 offset:31744
	ds_read_b64_tr_b16 v[74:75], v168 offset:32256
	ds_read_b128 v[132:135], v188 offset:3072
	v_add_f32_e32 v136, v78, v140
	v_add_f32_e32 v136, v79, v136
	v_add_f32_e32 v136, 0, v136
	v_cvt_pk_bf16_f32 v146, v76, v77
	v_cvt_pk_bf16_f32 v147, v78, v79
	s_waitcnt lgkmcnt(0)
	v_mfma_f32_32x32x16_bf16 v[96:111], v[128:131], v[132:135], v[96:111]
	v_mfma_f32_32x32x16_bf16 v[48:63], v[156:159], v[170:173], v[48:63]
	ds_read_b64_tr_b16 v[76:77], v168 offset:32768
	ds_read_b64_tr_b16 v[78:79], v168 offset:33280
	v_exp_f32_e32 v80, v80
	v_exp_f32_e32 v81, v81
	v_mfma_f32_32x32x16_bf16 v[32:47], v[156:159], v[112:115], v[32:47]
	ds_read_b64_tr_b16 v[128:129], v168 offset:36864
	ds_read_b64_tr_b16 v[130:131], v168 offset:37376
	v_exp_f32_e32 v82, v82
	v_exp_f32_e32 v83, v83
	v_mfma_f32_32x32x16_bf16 v[48:63], v[152:155], v[116:119], v[48:63]
	ds_read_b64_tr_b16 v[112:113], v168 offset:33792
	ds_read_b64_tr_b16 v[114:115], v168 offset:34304
	v_exp_f32_e32 v84, v84
	v_exp_f32_e32 v85, v85
	v_mfma_f32_32x32x16_bf16 v[32:47], v[152:155], v[120:123], v[32:47]
	ds_read_b64_tr_b16 v[116:117], v168 offset:37888
	ds_read_b64_tr_b16 v[118:119], v168 offset:38400
	v_exp_f32_e32 v86, v86
	v_exp_f32_e32 v87, v87
	v_mfma_f32_32x32x16_bf16 v[48:63], v[148:151], v[124:127], v[48:63]
	ds_read_b64_tr_b16 v[120:121], v168 offset:34816
	ds_read_b64_tr_b16 v[122:123], v168 offset:35328
	v_exp_f32_e32 v88, v88
	v_exp_f32_e32 v89, v89
	v_mfma_f32_32x32x16_bf16 v[32:47], v[148:151], v[64:67], v[32:47]
	ds_read_b64_tr_b16 v[124:125], v168 offset:38912
	ds_read_b64_tr_b16 v[126:127], v168 offset:39424
	v_exp_f32_e32 v90, v90
	v_exp_f32_e32 v91, v91
	v_mfma_f32_32x32x16_bf16 v[48:63], v[144:147], v[68:71], v[48:63]
	ds_read_b64_tr_b16 v[64:65], v168 offset:35840
	ds_read_b64_tr_b16 v[66:67], v168 offset:36352
	v_exp_f32_e32 v92, v92
	v_exp_f32_e32 v93, v93
	v_mfma_f32_32x32x16_bf16 v[32:47], v[144:147], v[72:75], v[32:47]
	ds_read_b64_tr_b16 v[68:69], v168 offset:39936
	ds_read_b64_tr_b16 v[70:71], v168 offset:40448
	v_exp_f32_e32 v94, v94
	v_exp_f32_e32 v95, v95
	s_waitcnt lgkmcnt(14)
	v_mfma_f32_32x32x16_bf16 v[16:31], v[156:159], v[76:79], v[16:31]
	v_exp_f32_e32 v96, v96
	v_exp_f32_e32 v97, v97
	s_waitcnt lgkmcnt(12)
; #define SBAR() __builtin_amdgcn_sched_barrier(0)
;   #define PKW(P,B) cvtpk_s(P[B],P[B+1])
; template<int THRL,int VM,bool NOMAX> __device__ __forceinline__ void attn_unit(const bf16*Qb,const bf16*__restrict__ Kh,const bf16*__restrict__ Vh,bf16*Ob,const int NT,const int sp,float*wscr,char*shm){
;     ...
;   { float sacc=pB0[0]+pB0[1]; _Pragma("unroll") for(int r=2;r<16;++r)sacc+=pB0[r]; _Pragma("unroll") for(int r=0;r<16;++r)sacc+=pB1[r]; l_reg+=sacc;
;     pw0=(u32x4){PKW(pB0,0),PKW(pB0,2),PKW(pB0,4),PKW(pB0,6)};pw1=(u32x4){PKW(pB0,8),PKW(pB0,10),PKW(pB0,12),PKW(pB0,14)};pw2=(u32x4){PKW(pB1,0),PKW(pB1,2),PKW(pB1,4),PKW(pB1,6)};pw3=(u32x4){PKW(pB1,8),PKW(pB1,10),PKW(pB1,12),PKW(pB1,14)};
;     SBAR(); pv(o,vb0+VM*sl_cur,PAF(0),PAF(1),PAF(2),PAF(3)); if constexpr(VM==2) pv(o+2,vb0+VM*sl_cur+8192,PAF(0),PAF(1),PAF(2),PAF(3)); }
;     ...
;   {auto rr=__builtin_amdgcn_permlane32_swap(__float_as_uint(l_reg),__float_as_uint(l_reg),false,false);l_reg=__uint_as_float(rr[0])+__uint_as_float(rr[1]);}
;   if(hi==0)wsf[32+r32]=l_reg;asm volatile("s_waitcnt lgkmcnt(0)":::"memory");
	v_mfma_f32_32x32x16_bf16 v[0:15], v[156:159], v[128:131], v[0:15]
	v_exp_f32_e32 v98, v98
	v_exp_f32_e32 v99, v99
	s_waitcnt lgkmcnt(10)
	v_mfma_f32_32x32x16_bf16 v[16:31], v[152:155], v[112:115], v[16:31]
	v_exp_f32_e32 v100, v100
	v_exp_f32_e32 v101, v101
	s_waitcnt lgkmcnt(8)
	v_mfma_f32_32x32x16_bf16 v[0:15], v[152:155], v[116:119], v[0:15]
	v_exp_f32_e32 v102, v102
	v_exp_f32_e32 v103, v103
	s_waitcnt lgkmcnt(6)
	v_mfma_f32_32x32x16_bf16 v[16:31], v[148:151], v[120:123], v[16:31]
	v_exp_f32_e32 v104, v104
	v_exp_f32_e32 v105, v105
	s_waitcnt lgkmcnt(4)
	v_mfma_f32_32x32x16_bf16 v[0:15], v[148:151], v[124:127], v[0:15]
	v_exp_f32_e32 v106, v106
	v_exp_f32_e32 v107, v107
	s_waitcnt lgkmcnt(2)
	v_mfma_f32_32x32x16_bf16 v[16:31], v[144:147], v[64:67], v[16:31]
	v_exp_f32_e32 v108, v108
	v_exp_f32_e32 v109, v109
	s_waitcnt lgkmcnt(0)
	v_mfma_f32_32x32x16_bf16 v[0:15], v[144:147], v[68:71], v[0:15]
	v_exp_f32_e32 v110, v110
	v_exp_f32_e32 v111, v111
	v_add_f32_e32 v64, v80, v81
	v_add_f32_e32 v64, v82, v64
	v_add_f32_e32 v64, v83, v64
	v_add_f32_e32 v64, v84, v64
	v_add_f32_e32 v64, v85, v64
	v_add_f32_e32 v64, v86, v64
	v_add_f32_e32 v64, v87, v64
	v_add_f32_e32 v64, v88, v64
	v_add_f32_e32 v64, v89, v64
	v_add_f32_e32 v64, v90, v64
	v_add_f32_e32 v64, v91, v64
	v_add_f32_e32 v64, v92, v64
	v_add_f32_e32 v64, v93, v64
	v_add_f32_e32 v64, v94, v64
	v_add_f32_e32 v64, v95, v64
	v_add_f32_e32 v64, v64, v96
	v_add_f32_e32 v64, v97, v64
	v_add_f32_e32 v64, v98, v64
	v_add_f32_e32 v64, v99, v64
	v_add_f32_e32 v64, v100, v64
	v_add_f32_e32 v64, v101, v64
	v_add_f32_e32 v64, v102, v64
	v_add_f32_e32 v64, v103, v64
	v_add_f32_e32 v64, v104, v64
	v_add_f32_e32 v64, v105, v64
	v_add_f32_e32 v64, v106, v64
	v_add_f32_e32 v64, v107, v64
	v_add_f32_e32 v64, v108, v64
	v_add_f32_e32 v64, v109, v64
	v_add_f32_e32 v64, v110, v64
	v_add_f32_e32 v64, v111, v64
	v_add_f32_e32 v65, v174, v136
	v_add_f32_e32 v64, v65, v64
	v_cvt_pk_bf16_f32 v66, v80, v81
	v_cvt_pk_bf16_f32 v67, v82, v83
	v_cvt_pk_bf16_f32 v68, v84, v85
	v_cvt_pk_bf16_f32 v69, v86, v87
	v_cvt_pk_bf16_f32 v70, v88, v89
	v_cvt_pk_bf16_f32 v71, v90, v91
	v_cvt_pk_bf16_f32 v72, v92, v93
	v_cvt_pk_bf16_f32 v73, v94, v95
	v_cvt_pk_bf16_f32 v74, v96, v97
	v_cvt_pk_bf16_f32 v75, v98, v99
	v_cvt_pk_bf16_f32 v76, v100, v101
	v_cvt_pk_bf16_f32 v77, v102, v103
	v_cvt_pk_bf16_f32 v78, v104, v105
	v_cvt_pk_bf16_f32 v79, v106, v107
	v_cvt_pk_bf16_f32 v80, v108, v109
	v_cvt_pk_bf16_f32 v81, v110, v111
	v_add_u32_e32 v65, 0x4000, v176
	ds_read_b64_tr_b16 v[82:83],v65 offset:0
	ds_read_b64_tr_b16 v[84:85],v65 offset:512
	ds_read_b64_tr_b16 v[86:87],v65 offset:1024
	ds_read_b64_tr_b16 v[88:89],v65 offset:1536
	ds_read_b64_tr_b16 v[90:91],v65 offset:2048
	ds_read_b64_tr_b16 v[92:93],v65 offset:2560
	ds_read_b64_tr_b16 v[94:95],v65 offset:3072
	ds_read_b64_tr_b16 v[96:97],v65 offset:3584
	s_waitcnt lgkmcnt(0)
	s_nop 0
	v_mfma_f32_32x32x16_bf16 v[48:63], v[66:69], v[82:85], v[48:63]
	ds_read_b64_tr_b16 v[82:83],v65 offset:4096
	ds_read_b64_tr_b16 v[84:85],v65 offset:4608
	v_mfma_f32_32x32x16_bf16 v[48:63], v[70:73], v[86:89], v[48:63]
	ds_read_b64_tr_b16 v[86:87],v65 offset:5120
	ds_read_b64_tr_b16 v[88:89],v65 offset:5632
	v_mfma_f32_32x32x16_bf16 v[48:63], v[74:77], v[90:93], v[48:63]
	ds_read_b64_tr_b16 v[90:91],v65 offset:6144
	ds_read_b64_tr_b16 v[92:93],v65 offset:6656
	ds_read_b64_tr_b16 v[98:99],v65 offset:7168
	ds_read_b64_tr_b16 v[100:101],v65 offset:7680
	s_waitcnt lgkmcnt(0)
	v_mfma_f32_32x32x16_bf16 v[48:63], v[78:81], v[94:97], v[48:63]
	v_mfma_f32_32x32x16_bf16 v[32:47], v[66:69], v[82:85], v[32:47]
	v_add_u32_e32 v65, 0x6000, v176
	ds_read_b64_tr_b16 v[82:83],v65 offset:0
	ds_read_b64_tr_b16 v[84:85],v65 offset:512
	v_mfma_f32_32x32x16_bf16 v[32:47], v[70:73], v[86:89], v[32:47]
	ds_read_b64_tr_b16 v[86:87],v65 offset:1024
	ds_read_b64_tr_b16 v[88:89],v65 offset:1536
	v_mfma_f32_32x32x16_bf16 v[32:47], v[74:77], v[90:93], v[32:47]
	ds_read_b64_tr_b16 v[90:91],v65 offset:2048
	ds_read_b64_tr_b16 v[92:93],v65 offset:2560
	ds_read_b64_tr_b16 v[94:95],v65 offset:3072
	ds_read_b64_tr_b16 v[96:97],v65 offset:3584
	s_waitcnt lgkmcnt(0)
	v_mfma_f32_32x32x16_bf16 v[32:47], v[78:81], v[98:101], v[32:47]
	v_mfma_f32_32x32x16_bf16 v[16:31], v[66:69], v[82:85], v[16:31]
	ds_read_b64_tr_b16 v[82:83],v65 offset:4096
	ds_read_b64_tr_b16 v[84:85],v65 offset:4608
	v_mfma_f32_32x32x16_bf16 v[16:31], v[70:73], v[86:89], v[16:31]
	ds_read_b64_tr_b16 v[86:87],v65 offset:5120
	ds_read_b64_tr_b16 v[88:89],v65 offset:5632
	v_mfma_f32_32x32x16_bf16 v[16:31], v[74:77], v[90:93], v[16:31]
	ds_read_b64_tr_b16 v[90:91],v65 offset:6144
	ds_read_b64_tr_b16 v[92:93],v65 offset:6656
	ds_read_b64_tr_b16 v[98:99],v65 offset:7168
	ds_read_b64_tr_b16 v[100:101],v65 offset:7680
	s_waitcnt lgkmcnt(0)
	v_mfma_f32_32x32x16_bf16 v[16:31], v[78:81], v[94:97], v[16:31]
	v_mfma_f32_32x32x16_bf16 v[0:15], v[66:69], v[82:85], v[0:15]
	v_mov_b32_e32 v65, v64
	s_nop 1
	v_permlane32_swap_b32_e32 v64, v65
	v_cmp_gt_u32_e32 vcc, 32, v187
	v_mfma_f32_32x32x16_bf16 v[0:15], v[70:73], v[86:89], v[0:15]
	v_mfma_f32_32x32x16_bf16 v[0:15], v[74:77], v[90:93], v[0:15]
	v_mfma_f32_32x32x16_bf16 v[0:15], v[78:81], v[98:101], v[0:15]
	s_and_saveexec_b64 s[16:17], vcc
	s_cbranch_execz .LBB0_859
	v_add_f32_e32 v64, v64, v65
	v_lshl_add_u32 v65, v186, 2, s34
	ds_write_b32 v65, v64 offset:128
	s_branch .LBB0_859

.LBB0_874:
	v_lshl_add_u32 v206, s89, 1, v188
	ds_read_b64_tr_b16 v[194:195], v206 offset:24576
	ds_read_b64_tr_b16 v[196:197], v206 offset:25088
	v_add_f32_e32 v108, v80, v81
	ds_read_b128 v[246:249], v168 offset:1024
	v_add_f32_e32 v108, v82, v108
	v_add_f32_e32 v108, v83, v108
	v_add_f32_e32 v108, v84, v108
	v_add_f32_e32 v108, v85, v108
	v_cvt_pk_bf16_f32 v156, v80, v81
	v_cvt_pk_bf16_f32 v157, v82, v83
	v_mfma_f32_32x32x16_bf16 v[112:127], v[100:103], v[242:245], 0
	ds_read_b64_tr_b16 v[80:81], v206 offset:28672
	ds_read_b64_tr_b16 v[82:83], v206 offset:29184
	v_add_f32_e32 v104, v86, v108
	v_add_f32_e32 v104, v87, v104
	v_add_f32_e32 v104, v88, v104
	v_add_f32_e32 v144, v89, v104
	v_mfma_f32_32x32x16_bf16 v[96:111], v[96:99], v[242:245], 0
	v_cvt_pk_bf16_f32 v158, v84, v85
	v_cvt_pk_bf16_f32 v159, v86, v87
	ds_read_b64_tr_b16 v[84:85], v206 offset:25600
	ds_read_b64_tr_b16 v[86:87], v206 offset:26112
	ds_read_b128 v[242:245], v168 offset:2048
	v_add_f32_e32 v144, v90, v144
	v_add_f32_e32 v144, v91, v144
	v_add_f32_e32 v144, v92, v144
	v_add_f32_e32 v144, v93, v144
	v_cvt_pk_bf16_f32 v152, v88, v89
	v_cvt_pk_bf16_f32 v153, v90, v91
	s_waitcnt lgkmcnt(5)
	v_mfma_f32_32x32x16_bf16 v[112:127], v[164:167], v[246:249], v[112:127]
	ds_read_b64_tr_b16 v[88:89], v206 offset:29696
	ds_read_b64_tr_b16 v[90:91], v206 offset:30208
	v_add_f32_e32 v144, v94, v144
	v_add_f32_e32 v144, v95, v144
	v_add_f32_e32 v144, v64, v144
	v_add_f32_e32 v144, v65, v144
	v_mfma_f32_32x32x16_bf16 v[96:111], v[160:163], v[246:249], v[96:111]
	v_cvt_pk_bf16_f32 v154, v92, v93
	v_cvt_pk_bf16_f32 v155, v94, v95
	ds_read_b64_tr_b16 v[92:93], v206 offset:26624
	ds_read_b64_tr_b16 v[94:95], v206 offset:27136
	ds_read_b128 v[246:249], v168 offset:3072
	v_add_f32_e32 v144, v66, v144
	v_add_f32_e32 v144, v67, v144
	v_add_f32_e32 v144, v68, v144
	v_add_f32_e32 v144, v69, v144
	v_cvt_pk_bf16_f32 v148, v64, v65
	v_cvt_pk_bf16_f32 v149, v66, v67
	s_waitcnt lgkmcnt(5)
	v_mfma_f32_32x32x16_bf16 v[112:127], v[140:143], v[242:245], v[112:127]
	ds_read_b64_tr_b16 v[198:199], v206 offset:30720
	ds_read_b64_tr_b16 v[200:201], v206 offset:31232
	v_add_f32_e32 v140, v70, v144
	v_add_f32_e32 v140, v71, v140
	v_add_f32_e32 v140, v72, v140
	v_add_f32_e32 v140, v73, v140
	v_mfma_f32_32x32x16_bf16 v[96:111], v[136:139], v[242:245], v[96:111]
	v_cvt_pk_bf16_f32 v150, v68, v69
	v_cvt_pk_bf16_f32 v151, v70, v71
	ds_read_b64_tr_b16 v[202:203], v206 offset:27648
	ds_read_b64_tr_b16 v[204:205], v206 offset:28160
	v_add_f32_e32 v68, v74, v140
	v_add_f32_e32 v68, v75, v68
	v_add_f32_e32 v68, v76, v68
	v_add_f32_e32 v68, v77, v68
	v_cvt_pk_bf16_f32 v144, v72, v73
	v_cvt_pk_bf16_f32 v145, v74, v75
	s_waitcnt lgkmcnt(4)
	v_mfma_f32_32x32x16_bf16 v[112:127], v[132:135], v[246:249], v[112:127]
	ds_read_b64_tr_b16 v[72:73], v206 offset:31744
	ds_read_b64_tr_b16 v[74:75], v206 offset:32256
	v_add_f32_e32 v68, v78, v68
	v_add_f32_e32 v68, v79, v68
	v_add_f32_e32 v68, 0, v68
	v_cvt_pk_bf16_f32 v146, v76, v77
	v_mfma_f32_32x32x16_bf16 v[96:111], v[128:131], v[246:249], v[96:111]
	v_cvt_pk_bf16_f32 v147, v78, v79
	s_add_i32 s88, s87, s17
	v_lshl_add_u64 v[64:65], v[180:181], 0, s[56:57]
	s_mov_b32 s89, m0
	s_mov_b32 m0, s88
	s_nop 0
	global_load_lds_dwordx4 v[64:65], off
	s_mov_b32 m0, s89
	s_lshl_b32 s88, s86, 1
	v_lshl_add_u64 v[64:65], v[178:179], 0, s[56:57]
	s_add_i32 s88, s88, s16
	s_mov_b32 s89, m0
	s_mov_b32 m0, s88
	s_nop 0
	global_load_lds_dwordx4 v[64:65], off
	s_mov_b32 m0, s89
	v_lshl_add_u64 v[64:65], v[176:177], 0, s[56:57]
	s_addk_i32 s88, 0x2000
	s_mov_b32 s89, m0
	s_mov_b32 m0, s88
	s_nop 0
	global_load_lds_dwordx4 v[64:65], off
	s_mov_b32 m0, s89
	v_add_f32_e32 v193, v193, v68
	v_mfma_f32_32x32x16_bf16 v[48:63], v[156:159], v[194:197], v[48:63]
	ds_read_b64_tr_b16 v[76:77], v206 offset:32768
	ds_read_b64_tr_b16 v[78:79], v206 offset:33280
	v_exp_f32_e32 v112, v112
	v_exp_f32_e32 v113, v113
	v_mfma_f32_32x32x16_bf16 v[32:47], v[156:159], v[80:83], v[32:47]
	ds_read_b64_tr_b16 v[194:195], v206 offset:36864
	ds_read_b64_tr_b16 v[196:197], v206 offset:37376
	v_exp_f32_e32 v114, v114
	v_exp_f32_e32 v115, v115
	v_add_u32_e32 v128, s86, v189
	v_mfma_f32_32x32x16_bf16 v[48:63], v[152:155], v[84:87], v[48:63]
	ds_read_b64_tr_b16 v[80:81], v206 offset:33792
	ds_read_b64_tr_b16 v[82:83], v206 offset:34304
	v_exp_f32_e32 v116, v116
	v_exp_f32_e32 v117, v117
	v_mfma_f32_32x32x16_bf16 v[32:47], v[152:155], v[88:91], v[32:47]
	ds_read_b64_tr_b16 v[84:85], v206 offset:37888
	ds_read_b64_tr_b16 v[86:87], v206 offset:38400
	v_exp_f32_e32 v118, v118
	v_exp_f32_e32 v119, v119
	v_mfma_f32_32x32x16_bf16 v[48:63], v[148:151], v[92:95], v[48:63]
	ds_read_b64_tr_b16 v[88:89], v206 offset:34816
	ds_read_b64_tr_b16 v[90:91], v206 offset:35328
	v_exp_f32_e32 v120, v120
	v_exp_f32_e32 v121, v121
	s_waitcnt lgkmcnt(10)
	v_mfma_f32_32x32x16_bf16 v[32:47], v[148:151], v[198:201], v[32:47]
	ds_read_b64_tr_b16 v[92:93], v206 offset:38912
	ds_read_b64_tr_b16 v[94:95], v206 offset:39424
	v_exp_f32_e32 v122, v122
	v_exp_f32_e32 v123, v123
	v_mfma_f32_32x32x16_bf16 v[48:63], v[144:147], v[202:205], v[48:63]
	ds_read_b64_tr_b16 v[198:199], v206 offset:35840
	ds_read_b64_tr_b16 v[200:201], v206 offset:36352
	v_exp_f32_e32 v124, v124
	v_exp_f32_e32 v125, v125
	v_mfma_f32_32x32x16_bf16 v[32:47], v[144:147], v[72:75], v[32:47]
	ds_read_b64_tr_b16 v[202:203], v206 offset:39936
	ds_read_b64_tr_b16 v[204:205], v206 offset:40448
	v_exp_f32_e32 v126, v126
	v_exp_f32_e32 v127, v127
	ds_read_b128 v[68:71], v128
	s_waitcnt lgkmcnt(13)
	v_mfma_f32_32x32x16_bf16 v[16:31], v[156:159], v[76:79], v[16:31]
	v_exp_f32_e32 v96, v96
	v_exp_f32_e32 v97, v97
	ds_read_b128 v[64:67], v128 offset:512
	v_mfma_f32_32x32x16_bf16 v[0:15], v[156:159], v[194:197], v[0:15]
	v_exp_f32_e32 v98, v98
	v_exp_f32_e32 v99, v99
	ds_read_b128 v[164:167], v128 offset:2048
	s_waitcnt lgkmcnt(11)
	v_mfma_f32_32x32x16_bf16 v[16:31], v[152:155], v[80:83], v[16:31]
	v_exp_f32_e32 v100, v100
	v_exp_f32_e32 v101, v101
	ds_read_b128 v[140:143], v128 offset:2560
	v_mfma_f32_32x32x16_bf16 v[0:15], v[152:155], v[84:87], v[0:15]
	v_exp_f32_e32 v102, v102
	v_exp_f32_e32 v103, v103
	ds_read_b128 v[160:163], v128 offset:4096
	s_waitcnt lgkmcnt(9)
	v_mfma_f32_32x32x16_bf16 v[16:31], v[148:151], v[88:91], v[16:31]
	v_exp_f32_e32 v104, v104
	v_exp_f32_e32 v105, v105
	ds_read_b128 v[132:135], v128 offset:4608
	v_mfma_f32_32x32x16_bf16 v[0:15], v[148:151], v[92:95], v[0:15]
	v_exp_f32_e32 v106, v106
	v_exp_f32_e32 v107, v107
	ds_read_b128 v[136:139], v128 offset:6144
	s_waitcnt lgkmcnt(7)
	v_mfma_f32_32x32x16_bf16 v[16:31], v[144:147], v[198:201], v[16:31]
	v_exp_f32_e32 v108, v108
	v_exp_f32_e32 v109, v109
	ds_read_b128 v[128:131], v128 offset:6656
	v_mfma_f32_32x32x16_bf16 v[0:15], v[144:147], v[202:205], v[0:15]
	ds_read_b128 v[242:245], v168
	v_exp_f32_e32 v110, v110
	v_exp_f32_e32 v111, v111
	s_waitcnt vmcnt(3) lgkmcnt(0)
	s_barrier
	s_add_i32 s88, s86, 0x2000
	s_cmpk_lg_i32 s86, 0x4000
	s_cselect_b32 s88, s88, 0
	v_lshl_add_u32 v206, s87, 1, v188
	ds_read_b64_tr_b16 v[194:195], v206 offset:24576
	ds_read_b64_tr_b16 v[196:197], v206 offset:25088
	ds_read_b128 v[246:249], v168 offset:1024
	v_add_f32_e32 v76, v112, v113
	v_add_f32_e32 v76, v114, v76
	v_add_f32_e32 v76, v115, v76
	v_add_f32_e32 v76, v116, v76
	v_mfma_f32_32x32x16_bf16 v[80:95], v[68:71], v[242:245], 0
	v_add_f32_e32 v76, v117, v76
	v_cvt_pk_bf16_f32 v156, v112, v113
	v_cvt_pk_bf16_f32 v157, v114, v115
	ds_read_b64_tr_b16 v[112:113], v206 offset:28672
	ds_read_b64_tr_b16 v[114:115], v206 offset:29184
	v_add_f32_e32 v72, v118, v76
	v_add_f32_e32 v72, v119, v72
	v_add_f32_e32 v72, v120, v72
	v_add_f32_e32 v144, v121, v72
	v_mfma_f32_32x32x16_bf16 v[64:79], v[64:67], v[242:245], 0
	v_cvt_pk_bf16_f32 v158, v116, v117
	v_cvt_pk_bf16_f32 v159, v118, v119
	ds_read_b64_tr_b16 v[116:117], v206 offset:25600
	ds_read_b64_tr_b16 v[118:119], v206 offset:26112
	ds_read_b128 v[242:245], v168 offset:2048
	v_add_f32_e32 v144, v122, v144
	v_add_f32_e32 v144, v123, v144
	v_add_f32_e32 v144, v124, v144
	v_add_f32_e32 v144, v125, v144
	s_waitcnt lgkmcnt(5)
	v_mfma_f32_32x32x16_bf16 v[80:95], v[164:167], v[246:249], v[80:95]
	v_cvt_pk_bf16_f32 v152, v120, v121
	v_cvt_pk_bf16_f32 v153, v122, v123
	ds_read_b64_tr_b16 v[120:121], v206 offset:29696
	ds_read_b64_tr_b16 v[122:123], v206 offset:30208
	v_add_f32_e32 v144, v126, v144
	v_add_f32_e32 v144, v127, v144
	v_add_f32_e32 v144, v96, v144
	v_add_f32_e32 v144, v97, v144
	v_mfma_f32_32x32x16_bf16 v[64:79], v[140:143], v[246:249], v[64:79]
	v_cvt_pk_bf16_f32 v154, v124, v125
	v_cvt_pk_bf16_f32 v155, v126, v127
	ds_read_b64_tr_b16 v[124:125], v206 offset:26624
	ds_read_b64_tr_b16 v[126:127], v206 offset:27136
	ds_read_b128 v[246:249], v168 offset:3072
	v_add_f32_e32 v144, v98, v144
	v_add_f32_e32 v144, v99, v144
	v_add_f32_e32 v144, v100, v144
	v_add_f32_e32 v144, v101, v144
	s_waitcnt lgkmcnt(5)
	v_mfma_f32_32x32x16_bf16 v[80:95], v[160:163], v[242:245], v[80:95]
	v_cvt_pk_bf16_f32 v148, v96, v97
	v_cvt_pk_bf16_f32 v149, v98, v99
	ds_read_b64_tr_b16 v[198:199], v206 offset:30720
	ds_read_b64_tr_b16 v[200:201], v206 offset:31232
	v_add_f32_e32 v140, v102, v144
	v_add_f32_e32 v140, v103, v140
	v_add_f32_e32 v140, v104, v140
	v_add_f32_e32 v140, v105, v140
	v_mfma_f32_32x32x16_bf16 v[64:79], v[132:135], v[242:245], v[64:79]
	v_cvt_pk_bf16_f32 v150, v100, v101
	v_cvt_pk_bf16_f32 v151, v102, v103
	ds_read_b64_tr_b16 v[202:203], v206 offset:27648
	ds_read_b64_tr_b16 v[204:205], v206 offset:28160
	v_add_f32_e32 v100, v106, v140
	v_add_f32_e32 v100, v107, v100
	v_add_f32_e32 v100, v108, v100
	v_add_f32_e32 v100, v109, v100
	s_waitcnt lgkmcnt(4)
	v_mfma_f32_32x32x16_bf16 v[80:95], v[136:139], v[246:249], v[80:95]
	v_cvt_pk_bf16_f32 v144, v104, v105
	v_cvt_pk_bf16_f32 v145, v106, v107
	ds_read_b64_tr_b16 v[104:105], v206 offset:31744
	ds_read_b64_tr_b16 v[106:107], v206 offset:32256
	v_add_f32_e32 v100, v110, v100
	v_add_f32_e32 v100, v111, v100
	v_add_f32_e32 v100, 0, v100
	v_cvt_pk_bf16_f32 v146, v108, v109
	v_mfma_f32_32x32x16_bf16 v[64:79], v[128:131], v[246:249], v[64:79]
	v_cvt_pk_bf16_f32 v147, v110, v111
	s_add_i32 s87, s86, s17
	s_mov_b32 s89, m0
	s_mov_b32 m0, s87
	s_nop 0
	global_load_lds_dwordx4 v[180:181], off
	s_mov_b32 m0, s89
	s_lshl_b32 s87, s88, 1
	s_add_i32 s87, s87, s16
	s_mov_b32 s89, m0
	s_mov_b32 m0, s87
	s_nop 0
	global_load_lds_dwordx4 v[178:179], off
	s_mov_b32 m0, s89
	s_addk_i32 s87, 0x2000
	s_mov_b32 s89, m0
	s_mov_b32 m0, s87
	s_nop 0
	global_load_lds_dwordx4 v[176:177], off
	s_mov_b32 m0, s89
	v_add_f32_e32 v193, v193, v100
	v_mfma_f32_32x32x16_bf16 v[48:63], v[156:159], v[194:197], v[48:63]
	ds_read_b64_tr_b16 v[108:109], v206 offset:32768
	ds_read_b64_tr_b16 v[110:111], v206 offset:33280
	v_exp_f32_e32 v80, v80
	v_exp_f32_e32 v81, v81
	v_mfma_f32_32x32x16_bf16 v[32:47], v[156:159], v[112:115], v[32:47]
	ds_read_b64_tr_b16 v[194:195], v206 offset:36864
	ds_read_b64_tr_b16 v[196:197], v206 offset:37376
	v_exp_f32_e32 v82, v82
	v_exp_f32_e32 v83, v83
	v_add_u32_e32 v128, s88, v189
	v_mfma_f32_32x32x16_bf16 v[48:63], v[152:155], v[116:119], v[48:63]
	ds_read_b64_tr_b16 v[112:113], v206 offset:33792
	ds_read_b64_tr_b16 v[114:115], v206 offset:34304
	v_exp_f32_e32 v84, v84
	v_exp_f32_e32 v85, v85
	v_mfma_f32_32x32x16_bf16 v[32:47], v[152:155], v[120:123], v[32:47]
	ds_read_b64_tr_b16 v[116:117], v206 offset:37888
	ds_read_b64_tr_b16 v[118:119], v206 offset:38400
	v_exp_f32_e32 v86, v86
	v_exp_f32_e32 v87, v87
	v_mfma_f32_32x32x16_bf16 v[48:63], v[148:151], v[124:127], v[48:63]
	ds_read_b64_tr_b16 v[120:121], v206 offset:34816
	ds_read_b64_tr_b16 v[122:123], v206 offset:35328
	v_exp_f32_e32 v88, v88
	v_exp_f32_e32 v89, v89
	s_waitcnt lgkmcnt(10)
	v_mfma_f32_32x32x16_bf16 v[32:47], v[148:151], v[198:201], v[32:47]
	ds_read_b64_tr_b16 v[124:125], v206 offset:38912
	ds_read_b64_tr_b16 v[126:127], v206 offset:39424
	v_exp_f32_e32 v90, v90
	v_exp_f32_e32 v91, v91
	v_mfma_f32_32x32x16_bf16 v[48:63], v[144:147], v[202:205], v[48:63]
	ds_read_b64_tr_b16 v[198:199], v206 offset:35840
	ds_read_b64_tr_b16 v[200:201], v206 offset:36352
	v_exp_f32_e32 v92, v92
	v_exp_f32_e32 v93, v93
	v_mfma_f32_32x32x16_bf16 v[32:47], v[144:147], v[104:107], v[32:47]
	ds_read_b64_tr_b16 v[202:203], v206 offset:39936
	ds_read_b64_tr_b16 v[204:205], v206 offset:40448
	v_exp_f32_e32 v94, v94
	v_exp_f32_e32 v95, v95
	ds_read_b128 v[100:103], v128
	s_waitcnt lgkmcnt(13)
	v_mfma_f32_32x32x16_bf16 v[16:31], v[156:159], v[108:111], v[16:31]
	v_exp_f32_e32 v64, v64
	v_exp_f32_e32 v65, v65
	ds_read_b128 v[96:99], v128 offset:512
	v_mfma_f32_32x32x16_bf16 v[0:15], v[156:159], v[194:197], v[0:15]
	v_exp_f32_e32 v66, v66
	v_exp_f32_e32 v67, v67
	ds_read_b128 v[164:167], v128 offset:2048
	s_waitcnt lgkmcnt(11)
	v_mfma_f32_32x32x16_bf16 v[16:31], v[152:155], v[112:115], v[16:31]
	v_exp_f32_e32 v68, v68
	v_exp_f32_e32 v69, v69
	ds_read_b128 v[160:163], v128 offset:2560
	v_mfma_f32_32x32x16_bf16 v[0:15], v[152:155], v[116:119], v[0:15]
	v_exp_f32_e32 v70, v70
	v_exp_f32_e32 v71, v71
	ds_read_b128 v[140:143], v128 offset:4096
	s_waitcnt lgkmcnt(9)
	v_mfma_f32_32x32x16_bf16 v[16:31], v[148:151], v[120:123], v[16:31]
	v_exp_f32_e32 v72, v72
	v_exp_f32_e32 v73, v73
	ds_read_b128 v[136:139], v128 offset:4608
	v_mfma_f32_32x32x16_bf16 v[0:15], v[148:151], v[124:127], v[0:15]
	v_exp_f32_e32 v74, v74
	v_exp_f32_e32 v75, v75
	ds_read_b128 v[132:135], v128 offset:6144
	s_waitcnt lgkmcnt(7)
	v_mfma_f32_32x32x16_bf16 v[16:31], v[144:147], v[198:201], v[16:31]
	v_exp_f32_e32 v76, v76
	v_exp_f32_e32 v77, v77
	ds_read_b128 v[128:131], v128 offset:6656
	v_mfma_f32_32x32x16_bf16 v[0:15], v[144:147], v[202:205], v[0:15]
	ds_read_b128 v[242:245], v168
	v_exp_f32_e32 v78, v78
	v_exp_f32_e32 v79, v79
	s_add_i32 s90, s88, 0x2000
	s_waitcnt vmcnt(3) lgkmcnt(0)
	s_barrier
; #define WAIT_BAR(N) asm volatile("s_waitcnt vmcnt(" #N ") lgkmcnt(0)\n\ts_barrier":::"memory")
;   #define DMA_K(t,slot) glds16(ksrc+(long)(t)*KVBLK*KVP,(unsigned)__builtin_amdgcn_readfirstlane(kdst+(slot)))
;   #define DMA_V(t,slot) do{ glds16(vsrc+(long)(t)*KVBLK*KVP,(unsigned)__builtin_amdgcn_readfirstlane(vdst+VM*(slot))); if constexpr(VM==2) glds16(vsrc+64+(long)(t)*KVBLK*KVP,(unsigned)__builtin_amdgcn_readfirstlane(vdst+VM*(slot)+8192)); }while(0)
;   #define RESC() do{ if(!NOMAX&&resc){ asm volatile("s_waitcnt lgkmcnt(0)":::"memory"); \
;       _Pragma("unroll") for(int d_=0;d_<2*VM;++d_) _Pragma("unroll") for(int r=0;r<16;++r)o[d_][r]*=wsf[crow(r,hi)]; } }while(0)
;   #define ROT() do{sl_prev=sl_cur;sl_cur=sl_next;sl_next=(sl_next==(NSLOT-1)*SLOTB)?0:sl_next+SLOTB;}while(0)
;   #define ENDW(tt) do{ if((tt)+3<NT){ if constexpr(VM==2){WAIT_BAR(3);}else{WAIT_BAR(2);} } else if((tt)+2<NT){ if constexpr(VM==2){WAIT_BAR(2);}else{WAIT_BAR(1);} } else {WAIT_BAR(0);} }while(0)
; template<int THRL,int VM,bool NOMAX> __device__ __forceinline__ void attn_unit(const bf16*Qb,const bf16*__restrict__ Kh,const bf16*__restrict__ Vh,bf16*Ob,const int NT,const int sp,float*wscr,char*shm){
;     ...
;   DMA_K(2,2*SLOTB);
;   WAIT_BAR(3);
;   qkt(pA0,pA1,Kbase,qr,negm,r32,hi);asm volatile("s_nop 15\n\ts_nop 7":"+v"(pA0),"+v"(pA1));
;   START(pA0,pA1);
;   _Pragma("unroll") for(int r=0;r<16;++r)pA1[r]=__builtin_amdgcn_exp2f(pA1[r]);
;   WAIT_BAR(0);
;   DMA_K(3,0);DMA_V(1,SLOTB);
;   ROT();
;   kload8(kf,kp0+sl_cur);
;   if constexpr(VM==2){WAIT_BAR(3);}else{WAIT_BAR(2);}
;   s16x4 vlo[8],vhi[8]; u32x4 pw0,pw1,pw2,pw3;
;     ...
;   int t=1;
;   for(;t+5<NT;t+=2){
;     STEP(pB0,pB1,pA0,pA1,t,true,true,true);     if constexpr(VM==2){WAIT_BAR(3);}else{WAIT_BAR(2);} RESC(); ROT();
;     STEP(pA0,pA1,pB0,pB1,t+1,true,true,true);   if constexpr(VM==2){WAIT_BAR(3);}else{WAIT_BAR(2);} RESC(); ROT();
;   }
;     ...
;   for(;t+1<NT;t+=2){
;     STEP(pB0,pB1,pA0,pA1,t,(t+3<NT),(t+1<NT),(t+1<NT));       ENDW(t);   RESC(); ROT();
;     STEP(pA0,pA1,pB0,pB1,t+1,(t+4<NT),(t+2<NT),(t+2<NT));     ENDW(t+1); RESC(); ROT();
	s_cmpk_lg_i32 s88, 0x4000
	s_mov_b32 s89, s86
	s_cselect_b32 s86, s90, 0
	s_add_i32 s85, s85, 2
	v_lshl_add_u64 v[176:177], v[176:177], 0, s[58:59]
	v_lshl_add_u64 v[178:179], v[178:179], 0, s[58:59]
	v_lshl_add_u64 v[180:181], v[180:181], 0, s[58:59]
	s_mov_b32 s87, s88
	s_cmp_lt_u32 s85, 57
	s_cbranch_scc1 .LBB0_874
	s_and_b32 s34, s34, 0x3fffffc0
	s_lshl_b32 s34, s34, 2
	s_add_i32 s34, s34, 0
	s_add_i32 s34, s34, 0x12000
	s_cmp_lg_u32 0, -1
	s_cselect_b32 s85, 0, 0
	s_add_i32 s86, s85, 0x6000
	v_add_u32_e32 v104, s86, v191
	v_add3_u32 v176, v104, v190, v192
	v_add_u32_e32 v177, 0x6000, v188
	ds_read_b64_tr_b16 v[178:179], v188 offset:40960
	ds_read_b64_tr_b16 v[180:181], v188 offset:41472
	v_add_f32_e32 v108, v80, v81
	ds_read_b128 v[104:107], v168
	v_add_f32_e32 v108, v82, v108
	v_add_f32_e32 v108, v83, v108
	v_add_f32_e32 v108, v84, v108
	v_add_f32_e32 v108, v85, v108
	v_cvt_pk_bf16_f32 v156, v80, v81
	v_cvt_pk_bf16_f32 v157, v82, v83
	s_waitcnt lgkmcnt(0)
	v_mfma_f32_32x32x16_bf16 v[112:127], v[100:103], v[104:107], 0
	ds_read_b64_tr_b16 v[80:81], v188 offset:45056
	ds_read_b64_tr_b16 v[82:83], v188 offset:45568
	ds_read_b128 v[100:103], v168
	v_add_f32_e32 v104, v86, v108
	v_add_f32_e32 v104, v87, v104
	v_add_f32_e32 v104, v88, v104
	v_add_f32_e32 v144, v89, v104
	v_cvt_pk_bf16_f32 v158, v84, v85
	v_cvt_pk_bf16_f32 v159, v86, v87
	s_waitcnt lgkmcnt(0)
	v_mfma_f32_32x32x16_bf16 v[96:111], v[96:99], v[100:103], 0
	ds_read_b64_tr_b16 v[84:85], v188 offset:41984
	ds_read_b64_tr_b16 v[86:87], v188 offset:42496
	ds_read_b128 v[194:197], v168 offset:1024
	v_add_f32_e32 v144, v90, v144
	v_add_f32_e32 v144, v91, v144
	v_add_f32_e32 v144, v92, v144
	v_add_f32_e32 v144, v93, v144
	v_cvt_pk_bf16_f32 v152, v88, v89
	v_cvt_pk_bf16_f32 v153, v90, v91
	s_waitcnt lgkmcnt(0)
	v_mfma_f32_32x32x16_bf16 v[112:127], v[164:167], v[194:197], v[112:127]
	ds_read_b64_tr_b16 v[88:89], v188 offset:46080
	ds_read_b64_tr_b16 v[90:91], v188 offset:46592
	ds_read_b128 v[164:167], v168 offset:1024
	v_add_f32_e32 v144, v94, v144
	v_add_f32_e32 v144, v95, v144
	v_add_f32_e32 v144, v64, v144
	v_add_f32_e32 v144, v65, v144
	v_cvt_pk_bf16_f32 v154, v92, v93
	v_cvt_pk_bf16_f32 v155, v94, v95
	s_waitcnt lgkmcnt(0)
	v_mfma_f32_32x32x16_bf16 v[96:111], v[160:163], v[164:167], v[96:111]
	ds_read_b64_tr_b16 v[194:195], v188 offset:43008
	ds_read_b64_tr_b16 v[196:197], v188 offset:43520
	ds_read_b128 v[92:95], v168 offset:2048
	v_add_f32_e32 v144, v66, v144
	v_add_f32_e32 v144, v67, v144
	v_add_f32_e32 v144, v68, v144
	v_add_f32_e32 v144, v69, v144
	v_cvt_pk_bf16_f32 v148, v64, v65
	v_cvt_pk_bf16_f32 v149, v66, v67
	s_waitcnt lgkmcnt(0)
	v_mfma_f32_32x32x16_bf16 v[112:127], v[140:143], v[92:95], v[112:127]
	ds_read_b64_tr_b16 v[140:141], v188 offset:47104
	ds_read_b64_tr_b16 v[142:143], v188 offset:47616
	ds_read_b128 v[64:67], v168 offset:2048
	v_add_f32_e32 v92, v70, v144
	v_add_f32_e32 v92, v71, v92
	v_add_f32_e32 v92, v72, v92
	v_add_f32_e32 v92, v73, v92
	v_cvt_pk_bf16_f32 v150, v68, v69
	v_cvt_pk_bf16_f32 v151, v70, v71
	s_waitcnt lgkmcnt(0)
	v_mfma_f32_32x32x16_bf16 v[96:111], v[136:139], v[64:67], v[96:111]
	ds_read_b64_tr_b16 v[136:137], v188 offset:44032
	ds_read_b64_tr_b16 v[138:139], v188 offset:44544
	ds_read_b128 v[64:67], v168 offset:3072
	v_add_f32_e32 v68, v74, v92
	v_add_f32_e32 v68, v75, v68
	v_add_f32_e32 v68, v76, v68
	v_add_f32_e32 v68, v77, v68
	v_cvt_pk_bf16_f32 v144, v72, v73
	v_cvt_pk_bf16_f32 v145, v74, v75
	s_waitcnt lgkmcnt(0)
	v_mfma_f32_32x32x16_bf16 v[112:127], v[132:135], v[64:67], v[112:127]
	ds_read_b64_tr_b16 v[72:73], v188 offset:48128
	ds_read_b64_tr_b16 v[74:75], v188 offset:48640
	ds_read_b128 v[64:67], v168 offset:3072
	v_add_f32_e32 v68, v78, v68
	v_add_f32_e32 v68, v79, v68
	v_add_f32_e32 v68, 0, v68
	v_cvt_pk_bf16_f32 v146, v76, v77
	v_cvt_pk_bf16_f32 v147, v78, v79
	s_waitcnt lgkmcnt(0)
	v_mfma_f32_32x32x16_bf16 v[96:111], v[128:131], v[64:67], v[96:111]
	s_add_i32 s85, s85, s35
	v_lshl_add_u64 v[64:65], v[174:175], 0, s[60:61]
	s_add_i32 s35, s85, 0x4000
	s_mov_b32 s86, m0
	s_mov_b32 m0, s35
	s_nop 0
	global_load_lds_dwordx4 v[64:65], off
	s_mov_b32 m0, s86
	v_lshl_add_u64 v[64:65], v[170:171], 0, s[62:63]
	s_mov_b32 s35, m0
	s_mov_b32 m0, s16
	s_nop 0
	global_load_lds_dwordx4 v[64:65], off
	s_mov_b32 m0, s35
	v_lshl_add_u64 v[64:65], v[172:173], 0, s[62:63]
	s_add_i32 s35, s16, 0x2000
	s_mov_b32 s86, m0
	s_mov_b32 m0, s35
	s_nop 0
	global_load_lds_dwordx4 v[64:65], off
	s_mov_b32 m0, s86
	v_add_f32_e32 v198, v193, v68
	v_mfma_f32_32x32x16_bf16 v[48:63], v[156:159], v[178:181], v[48:63]
	ds_read_b64_tr_b16 v[76:77], v188 offset:49152
	ds_read_b64_tr_b16 v[78:79], v188 offset:49664
	v_exp_f32_e32 v112, v112
	v_exp_f32_e32 v113, v113
	v_mfma_f32_32x32x16_bf16 v[32:47], v[156:159], v[80:83], v[32:47]
	ds_read_b64_tr_b16 v[128:129], v188 offset:53248
	ds_read_b64_tr_b16 v[130:131], v188 offset:53760
	v_exp_f32_e32 v114, v114
	v_exp_f32_e32 v115, v115
	ds_read_b128 v[68:71], v189
	ds_read_b128 v[64:67], v189 offset:512
	v_mfma_f32_32x32x16_bf16 v[48:63], v[152:155], v[84:87], v[48:63]
	ds_read_b64_tr_b16 v[132:133], v188 offset:50176
	ds_read_b64_tr_b16 v[134:135], v188 offset:50688
	v_exp_f32_e32 v116, v116
	v_exp_f32_e32 v117, v117
	ds_read_b128 v[164:167], v189 offset:2048
	ds_read_b128 v[92:95], v189 offset:2560
	v_mfma_f32_32x32x16_bf16 v[32:47], v[152:155], v[88:91], v[32:47]
	ds_read_b64_tr_b16 v[178:179], v188 offset:54272
	ds_read_b64_tr_b16 v[180:181], v188 offset:54784
	v_exp_f32_e32 v118, v118
	v_exp_f32_e32 v119, v119
	ds_read_b128 v[160:163], v189 offset:4096
	ds_read_b128 v[84:87], v189 offset:4608
	v_mfma_f32_32x32x16_bf16 v[48:63], v[148:151], v[194:197], v[48:63]
	ds_read_b64_tr_b16 v[190:191], v188 offset:51200
	ds_read_b64_tr_b16 v[192:193], v188 offset:51712
	v_exp_f32_e32 v120, v120
	v_exp_f32_e32 v121, v121
	ds_read_b128 v[88:91], v189 offset:6144
	ds_read_b128 v[80:83], v189 offset:6656
	v_mfma_f32_32x32x16_bf16 v[32:47], v[148:151], v[140:143], v[32:47]
	ds_read_b64_tr_b16 v[194:195], v188 offset:55296
	ds_read_b64_tr_b16 v[196:197], v188 offset:55808
	v_exp_f32_e32 v122, v122
	v_exp_f32_e32 v123, v123
	v_mfma_f32_32x32x16_bf16 v[48:63], v[144:147], v[136:139], v[48:63]
	ds_read_b64_tr_b16 v[140:141], v188 offset:52224
	ds_read_b64_tr_b16 v[142:143], v188 offset:52736
	v_exp_f32_e32 v124, v124
	v_exp_f32_e32 v125, v125
	v_mfma_f32_32x32x16_bf16 v[32:47], v[144:147], v[72:75], v[32:47]
	ds_read_b64_tr_b16 v[136:137], v188 offset:56320
	ds_read_b64_tr_b16 v[138:139], v188 offset:56832
	v_exp_f32_e32 v126, v126
	v_exp_f32_e32 v127, v127
	s_waitcnt lgkmcnt(14)
; #define WAIT_BAR(N) asm volatile("s_waitcnt vmcnt(" #N ") lgkmcnt(0)\n\ts_barrier":::"memory")
;   #define RESC() do{ if(!NOMAX&&resc){ asm volatile("s_waitcnt lgkmcnt(0)":::"memory"); \
;       _Pragma("unroll") for(int d_=0;d_<2*VM;++d_) _Pragma("unroll") for(int r=0;r<16;++r)o[d_][r]*=wsf[crow(r,hi)]; } }while(0)
;   #define ROT() do{sl_prev=sl_cur;sl_cur=sl_next;sl_next=(sl_next==(NSLOT-1)*SLOTB)?0:sl_next+SLOTB;}while(0)
;   #define ENDW(tt) do{ if((tt)+3<NT){ if constexpr(VM==2){WAIT_BAR(3);}else{WAIT_BAR(2);} } else if((tt)+2<NT){ if constexpr(VM==2){WAIT_BAR(2);}else{WAIT_BAR(1);} } else {WAIT_BAR(0);} }while(0)
; template<int THRL,int VM,bool NOMAX> __device__ __forceinline__ void attn_unit(const bf16*Qb,const bf16*__restrict__ Kh,const bf16*__restrict__ Vh,bf16*Ob,const int NT,const int sp,float*wscr,char*shm){
;     ...
;   int t=1;
;   for(;t+5<NT;t+=2){
;     STEP(pB0,pB1,pA0,pA1,t,true,true,true);     if constexpr(VM==2){WAIT_BAR(3);}else{WAIT_BAR(2);} RESC(); ROT();
;     STEP(pA0,pA1,pB0,pB1,t+1,true,true,true);   if constexpr(VM==2){WAIT_BAR(3);}else{WAIT_BAR(2);} RESC(); ROT();
;   }
;     ...
;   for(;t+1<NT;t+=2){
;     STEP(pB0,pB1,pA0,pA1,t,(t+3<NT),(t+1<NT),(t+1<NT));       ENDW(t);   RESC(); ROT();
;     STEP(pA0,pA1,pB0,pB1,t+1,(t+4<NT),(t+2<NT),(t+2<NT));     ENDW(t+1); RESC(); ROT();
	v_mfma_f32_32x32x16_bf16 v[16:31], v[156:159], v[76:79], v[16:31]
	v_exp_f32_e32 v96, v96
	v_exp_f32_e32 v97, v97
	v_mfma_f32_32x32x16_bf16 v[0:15], v[156:159], v[128:131], v[0:15]
	v_exp_f32_e32 v98, v98
	v_exp_f32_e32 v99, v99
	v_mfma_f32_32x32x16_bf16 v[16:31], v[152:155], v[132:135], v[16:31]
	v_exp_f32_e32 v100, v100
	v_exp_f32_e32 v101, v101
	s_waitcnt lgkmcnt(12)
	v_mfma_f32_32x32x16_bf16 v[0:15], v[152:155], v[178:181], v[0:15]
	v_exp_f32_e32 v102, v102
	v_exp_f32_e32 v103, v103
	s_waitcnt lgkmcnt(8)
	v_mfma_f32_32x32x16_bf16 v[16:31], v[148:151], v[190:193], v[16:31]
	v_exp_f32_e32 v104, v104
	v_exp_f32_e32 v105, v105
	s_waitcnt lgkmcnt(4)
	v_mfma_f32_32x32x16_bf16 v[0:15], v[148:151], v[194:197], v[0:15]
	v_exp_f32_e32 v106, v106
	v_exp_f32_e32 v107, v107
	s_waitcnt lgkmcnt(2)
	v_mfma_f32_32x32x16_bf16 v[16:31], v[144:147], v[140:143], v[16:31]
	v_exp_f32_e32 v108, v108
	v_exp_f32_e32 v109, v109
	s_waitcnt lgkmcnt(0)
	v_mfma_f32_32x32x16_bf16 v[0:15], v[144:147], v[136:139], v[0:15]
	v_exp_f32_e32 v110, v110
	v_exp_f32_e32 v111, v111
	s_waitcnt vmcnt(3) lgkmcnt(0)
	s_barrier
	ds_read_b64_tr_b16 v[178:179], v188 offset:57344
	ds_read_b64_tr_b16 v[180:181], v188 offset:57856
	v_add_f32_e32 v76, v112, v113
	ds_read_b128 v[72:75], v168
	v_add_f32_e32 v76, v114, v76
	v_add_f32_e32 v76, v115, v76
	v_add_f32_e32 v76, v116, v76
	v_add_f32_e32 v76, v117, v76
	v_cvt_pk_bf16_f32 v156, v112, v113
	v_cvt_pk_bf16_f32 v157, v114, v115
	s_waitcnt lgkmcnt(0)
	v_mfma_f32_32x32x16_bf16 v[128:143], v[68:71], v[72:75], 0
	ds_read_b64_tr_b16 v[112:113], v188 offset:61440
	ds_read_b64_tr_b16 v[114:115], v188 offset:61952
	ds_read_b128 v[68:71], v168
	v_add_f32_e32 v72, v118, v76
	v_add_f32_e32 v72, v119, v72
	v_add_f32_e32 v72, v120, v72
	v_add_f32_e32 v144, v121, v72
	s_waitcnt lgkmcnt(0)
	v_mfma_f32_32x32x16_bf16 v[64:79], v[64:67], v[68:71], 0
	v_cvt_pk_bf16_f32 v158, v116, v117
	v_cvt_pk_bf16_f32 v159, v118, v119
	ds_read_b64_tr_b16 v[116:117], v188 offset:58368
	ds_read_b64_tr_b16 v[118:119], v188 offset:58880
	ds_read_b128 v[190:193], v168 offset:1024
	v_add_f32_e32 v144, v122, v144
	v_add_f32_e32 v144, v123, v144
	v_add_f32_e32 v144, v124, v144
	v_add_f32_e32 v144, v125, v144
	v_cvt_pk_bf16_f32 v152, v120, v121
	v_cvt_pk_bf16_f32 v153, v122, v123
	s_waitcnt lgkmcnt(0)
	v_mfma_f32_32x32x16_bf16 v[128:143], v[164:167], v[190:193], v[128:143]
	ds_read_b64_tr_b16 v[120:121], v188 offset:62464
	ds_read_b64_tr_b16 v[122:123], v188 offset:62976
	ds_read_b128 v[164:167], v168 offset:1024
	v_add_f32_e32 v144, v126, v144
	v_add_f32_e32 v144, v127, v144
	v_add_f32_e32 v144, v96, v144
	v_add_f32_e32 v144, v97, v144
	s_waitcnt lgkmcnt(0)
	v_mfma_f32_32x32x16_bf16 v[64:79], v[92:95], v[164:167], v[64:79]
	v_cvt_pk_bf16_f32 v154, v124, v125
	v_cvt_pk_bf16_f32 v155, v126, v127
	ds_read_b64_tr_b16 v[92:93], v188 offset:59392
	ds_read_b64_tr_b16 v[94:95], v188 offset:59904
	ds_read_b128 v[124:127], v168 offset:2048
	v_add_f32_e32 v144, v98, v144
	v_add_f32_e32 v144, v99, v144
	v_add_f32_e32 v144, v100, v144
	v_add_f32_e32 v144, v101, v144
	v_cvt_pk_bf16_f32 v148, v96, v97
	v_cvt_pk_bf16_f32 v149, v98, v99
	s_waitcnt lgkmcnt(0)
	v_mfma_f32_32x32x16_bf16 v[128:143], v[160:163], v[124:127], v[128:143]
	ds_read_b64_tr_b16 v[96:97], v188 offset:63488
	ds_read_b64_tr_b16 v[98:99], v188 offset:64000
	ds_read_b128 v[124:127], v168 offset:2048
	v_add_f32_e32 v144, v102, v144
	v_add_f32_e32 v144, v103, v144
	v_add_f32_e32 v144, v104, v144
	v_add_f32_e32 v144, v105, v144
	s_waitcnt lgkmcnt(0)
	v_mfma_f32_32x32x16_bf16 v[64:79], v[84:87], v[124:127], v[64:79]
	v_cvt_pk_bf16_f32 v150, v100, v101
	v_cvt_pk_bf16_f32 v151, v102, v103
	ds_read_b64_tr_b16 v[100:101], v188 offset:60416
	ds_read_b64_tr_b16 v[102:103], v188 offset:60928
	ds_read_b128 v[84:87], v168 offset:3072
	v_add_f32_e32 v124, v106, v144
	v_add_f32_e32 v124, v107, v124
	v_add_f32_e32 v124, v108, v124
	v_add_f32_e32 v124, v109, v124
	v_cvt_pk_bf16_f32 v144, v104, v105
	v_cvt_pk_bf16_f32 v145, v106, v107
	s_waitcnt lgkmcnt(0)
	v_mfma_f32_32x32x16_bf16 v[128:143], v[88:91], v[84:87], v[128:143]
	ds_read_b64_tr_b16 v[88:89], v188 offset:64512
	ds_read_b64_tr_b16 v[90:91], v188 offset:65024
	ds_read_b128 v[84:87], v168 offset:3072
	v_add_f32_e32 v104, v110, v124
	v_add_f32_e32 v104, v111, v104
	v_add_f32_e32 v104, 0, v104
	v_cvt_pk_bf16_f32 v146, v108, v109
	s_waitcnt lgkmcnt(0)
; #define WAIT_BAR(N) asm volatile("s_waitcnt vmcnt(" #N ") lgkmcnt(0)\n\ts_barrier":::"memory")
;   #define RESC() do{ if(!NOMAX&&resc){ asm volatile("s_waitcnt lgkmcnt(0)":::"memory"); \
;       _Pragma("unroll") for(int d_=0;d_<2*VM;++d_) _Pragma("unroll") for(int r=0;r<16;++r)o[d_][r]*=wsf[crow(r,hi)]; } }while(0)
;   #define ROT() do{sl_prev=sl_cur;sl_cur=sl_next;sl_next=(sl_next==(NSLOT-1)*SLOTB)?0:sl_next+SLOTB;}while(0)
;   #define ENDW(tt) do{ if((tt)+3<NT){ if constexpr(VM==2){WAIT_BAR(3);}else{WAIT_BAR(2);} } else if((tt)+2<NT){ if constexpr(VM==2){WAIT_BAR(2);}else{WAIT_BAR(1);} } else {WAIT_BAR(0);} }while(0)
; template<int THRL,int VM,bool NOMAX> __device__ __forceinline__ void attn_unit(const bf16*Qb,const bf16*__restrict__ Kh,const bf16*__restrict__ Vh,bf16*Ob,const int NT,const int sp,float*wscr,char*shm){
;     ...
;   int t=1;
;   for(;t+5<NT;t+=2){
;     STEP(pB0,pB1,pA0,pA1,t,true,true,true);     if constexpr(VM==2){WAIT_BAR(3);}else{WAIT_BAR(2);} RESC(); ROT();
;     STEP(pA0,pA1,pB0,pB1,t+1,true,true,true);   if constexpr(VM==2){WAIT_BAR(3);}else{WAIT_BAR(2);} RESC(); ROT();
;   }
;     ...
;   for(;t+1<NT;t+=2){
;     STEP(pB0,pB1,pA0,pA1,t,(t+3<NT),(t+1<NT),(t+1<NT));       ENDW(t);   RESC(); ROT();
;     STEP(pA0,pA1,pB0,pB1,t+1,(t+4<NT),(t+2<NT),(t+2<NT));     ENDW(t+1); RESC(); ROT();
	v_mfma_f32_32x32x16_bf16 v[64:79], v[80:83], v[84:87], v[64:79]
	v_cvt_pk_bf16_f32 v147, v110, v111
	v_lshl_add_u64 v[80:81], v[174:175], 0, s[64:65]
	s_mov_b32 s86, m0
	s_mov_b32 m0, s17
	s_nop 0
	global_load_lds_dwordx4 v[80:81], off
	s_mov_b32 m0, s86
	v_lshl_add_u64 v[80:81], v[170:171], 0, s[66:67]
	s_add_i32 s17, s85, 0xa000
	s_mov_b32 s86, m0
	s_mov_b32 m0, s17
	s_nop 0
	global_load_lds_dwordx4 v[80:81], off
	s_mov_b32 m0, s86
	v_lshl_add_u64 v[80:81], v[172:173], 0, s[66:67]
	s_add_i32 s17, s85, 0xc000
	s_mov_b32 s86, m0
	s_mov_b32 m0, s17
	s_nop 0
	global_load_lds_dwordx4 v[80:81], off
	s_mov_b32 m0, s86
	v_add_f32_e32 v198, v198, v104
	v_mfma_f32_32x32x16_bf16 v[48:63], v[156:159], v[178:181], v[48:63]
	ds_read_b64_tr_b16 v[104:105], v177 offset:40960
	ds_read_b64_tr_b16 v[106:107], v177 offset:41472
	v_exp_f32_e32 v128, v128
	v_exp_f32_e32 v129, v129
	v_mfma_f32_32x32x16_bf16 v[32:47], v[156:159], v[112:115], v[32:47]
	ds_read_b64_tr_b16 v[108:109], v177 offset:45056
	ds_read_b64_tr_b16 v[110:111], v177 offset:45568
	v_exp_f32_e32 v130, v130
	v_exp_f32_e32 v131, v131
	ds_read_b128 v[84:87], v189 offset:8192
	ds_read_b128 v[80:83], v189 offset:8704
	v_mfma_f32_32x32x16_bf16 v[48:63], v[152:155], v[116:119], v[48:63]
	ds_read_b64_tr_b16 v[178:179], v177 offset:41984
	ds_read_b64_tr_b16 v[180:181], v177 offset:42496
	v_exp_f32_e32 v132, v132
	v_exp_f32_e32 v133, v133
	ds_read_b128 v[164:167], v189 offset:10240
	ds_read_b128 v[124:127], v189 offset:10752
	v_mfma_f32_32x32x16_bf16 v[32:47], v[152:155], v[120:123], v[32:47]
	ds_read_b64_tr_b16 v[190:191], v177 offset:46080
	ds_read_b64_tr_b16 v[192:193], v177 offset:46592
	v_exp_f32_e32 v134, v134
	v_exp_f32_e32 v135, v135
	ds_read_b128 v[160:163], v189 offset:12288
	ds_read_b128 v[116:119], v189 offset:12800
	v_mfma_f32_32x32x16_bf16 v[48:63], v[148:151], v[92:95], v[48:63]
	ds_read_b64_tr_b16 v[194:195], v177 offset:43008
	ds_read_b64_tr_b16 v[196:197], v177 offset:43520
	v_exp_f32_e32 v136, v136
	v_exp_f32_e32 v137, v137
	ds_read_b128 v[120:123], v189 offset:14336
	ds_read_b128 v[112:115], v189 offset:14848
	v_mfma_f32_32x32x16_bf16 v[32:47], v[148:151], v[96:99], v[32:47]
	ds_read_b64_tr_b16 v[92:93], v177 offset:47104
	ds_read_b64_tr_b16 v[94:95], v177 offset:47616
	v_exp_f32_e32 v138, v138
	v_exp_f32_e32 v139, v139
	v_mfma_f32_32x32x16_bf16 v[48:63], v[144:147], v[100:103], v[48:63]
	ds_read_b64_tr_b16 v[96:97], v177 offset:44032
	ds_read_b64_tr_b16 v[98:99], v177 offset:44544
	v_exp_f32_e32 v140, v140
	v_exp_f32_e32 v141, v141
	v_mfma_f32_32x32x16_bf16 v[32:47], v[144:147], v[88:91], v[32:47]
	ds_read_b64_tr_b16 v[100:101], v177 offset:48128
	ds_read_b64_tr_b16 v[102:103], v177 offset:48640
	v_exp_f32_e32 v142, v142
	v_exp_f32_e32 v143, v143
	s_waitcnt lgkmcnt(14)
	v_mfma_f32_32x32x16_bf16 v[16:31], v[156:159], v[104:107], v[16:31]
	v_exp_f32_e32 v64, v64
	v_exp_f32_e32 v65, v65
	v_mfma_f32_32x32x16_bf16 v[0:15], v[156:159], v[108:111], v[0:15]
	v_exp_f32_e32 v66, v66
	v_exp_f32_e32 v67, v67
	v_mfma_f32_32x32x16_bf16 v[16:31], v[152:155], v[178:181], v[16:31]
	v_exp_f32_e32 v68, v68
	v_exp_f32_e32 v69, v69
	s_waitcnt lgkmcnt(12)
	v_mfma_f32_32x32x16_bf16 v[0:15], v[152:155], v[190:193], v[0:15]
	v_exp_f32_e32 v70, v70
	v_exp_f32_e32 v71, v71
	s_waitcnt lgkmcnt(8)
	v_mfma_f32_32x32x16_bf16 v[16:31], v[148:151], v[194:197], v[16:31]
	v_exp_f32_e32 v72, v72
	v_exp_f32_e32 v73, v73
	s_waitcnt lgkmcnt(4)
	v_mfma_f32_32x32x16_bf16 v[0:15], v[148:151], v[92:95], v[0:15]
	v_exp_f32_e32 v74, v74
	v_exp_f32_e32 v75, v75
	s_waitcnt lgkmcnt(2)
	v_mfma_f32_32x32x16_bf16 v[16:31], v[144:147], v[96:99], v[16:31]
	v_exp_f32_e32 v76, v76
	v_exp_f32_e32 v77, v77
	s_waitcnt lgkmcnt(0)
	v_mfma_f32_32x32x16_bf16 v[0:15], v[144:147], v[100:103], v[0:15]
	v_exp_f32_e32 v78, v78
	v_exp_f32_e32 v79, v79
	s_waitcnt vmcnt(3) lgkmcnt(0)
	s_barrier
	ds_read_b64_tr_b16 v[178:179], v188 offset:24576
	ds_read_b64_tr_b16 v[180:181], v188 offset:25088
	v_add_f32_e32 v92, v128, v129
	ds_read_b128 v[88:91], v168
	v_add_f32_e32 v92, v130, v92
	v_add_f32_e32 v92, v131, v92
	v_add_f32_e32 v92, v132, v92
	v_add_f32_e32 v92, v133, v92
	v_cvt_pk_bf16_f32 v156, v128, v129
	v_cvt_pk_bf16_f32 v157, v130, v131
	s_waitcnt lgkmcnt(0)
	v_mfma_f32_32x32x16_bf16 v[96:111], v[84:87], v[88:91], 0
	ds_read_b64_tr_b16 v[128:129], v188 offset:28672
	ds_read_b64_tr_b16 v[130:131], v188 offset:29184
	ds_read_b128 v[84:87], v168
	v_add_f32_e32 v88, v134, v92
	v_add_f32_e32 v88, v135, v88
	v_add_f32_e32 v88, v136, v88
	v_add_f32_e32 v144, v137, v88
	v_cvt_pk_bf16_f32 v158, v132, v133
	v_cvt_pk_bf16_f32 v159, v134, v135
	s_waitcnt lgkmcnt(0)
	v_mfma_f32_32x32x16_bf16 v[80:95], v[80:83], v[84:87], 0
	ds_read_b64_tr_b16 v[132:133], v188 offset:25600
	ds_read_b64_tr_b16 v[134:135], v188 offset:26112
	ds_read_b128 v[190:193], v168 offset:1024
	v_add_f32_e32 v144, v138, v144
	v_add_f32_e32 v144, v139, v144
	v_add_f32_e32 v144, v140, v144
	v_add_f32_e32 v144, v141, v144
	v_cvt_pk_bf16_f32 v152, v136, v137
	v_cvt_pk_bf16_f32 v153, v138, v139
	s_waitcnt lgkmcnt(0)
	v_mfma_f32_32x32x16_bf16 v[96:111], v[164:167], v[190:193], v[96:111]
	ds_read_b64_tr_b16 v[136:137], v188 offset:29696
	ds_read_b64_tr_b16 v[138:139], v188 offset:30208
	ds_read_b128 v[164:167], v168 offset:1024
	v_add_f32_e32 v144, v142, v144
	v_add_f32_e32 v144, v143, v144
	v_add_f32_e32 v144, v64, v144
	v_add_f32_e32 v144, v65, v144
	v_cvt_pk_bf16_f32 v154, v140, v141
	v_cvt_pk_bf16_f32 v155, v142, v143
	s_waitcnt lgkmcnt(0)
; #define WAIT_BAR(N) asm volatile("s_waitcnt vmcnt(" #N ") lgkmcnt(0)\n\ts_barrier":::"memory")
;   #define RESC() do{ if(!NOMAX&&resc){ asm volatile("s_waitcnt lgkmcnt(0)":::"memory"); \
;       _Pragma("unroll") for(int d_=0;d_<2*VM;++d_) _Pragma("unroll") for(int r=0;r<16;++r)o[d_][r]*=wsf[crow(r,hi)]; } }while(0)
;   #define ROT() do{sl_prev=sl_cur;sl_cur=sl_next;sl_next=(sl_next==(NSLOT-1)*SLOTB)?0:sl_next+SLOTB;}while(0)
;   #define ENDW(tt) do{ if((tt)+3<NT){ if constexpr(VM==2){WAIT_BAR(3);}else{WAIT_BAR(2);} } else if((tt)+2<NT){ if constexpr(VM==2){WAIT_BAR(2);}else{WAIT_BAR(1);} } else {WAIT_BAR(0);} }while(0)
; template<int THRL,int VM,bool NOMAX> __device__ __forceinline__ void attn_unit(const bf16*Qb,const bf16*__restrict__ Kh,const bf16*__restrict__ Vh,bf16*Ob,const int NT,const int sp,float*wscr,char*shm){
;     ...
;   int t=1;
;   for(;t+5<NT;t+=2){
;     STEP(pB0,pB1,pA0,pA1,t,true,true,true);     if constexpr(VM==2){WAIT_BAR(3);}else{WAIT_BAR(2);} RESC(); ROT();
;     STEP(pA0,pA1,pB0,pB1,t+1,true,true,true);   if constexpr(VM==2){WAIT_BAR(3);}else{WAIT_BAR(2);} RESC(); ROT();
;   }
;     ...
;   for(;t+1<NT;t+=2){
;     STEP(pB0,pB1,pA0,pA1,t,(t+3<NT),(t+1<NT),(t+1<NT));       ENDW(t);   RESC(); ROT();
;     STEP(pA0,pA1,pB0,pB1,t+1,(t+4<NT),(t+2<NT),(t+2<NT));     ENDW(t+1); RESC(); ROT();
	v_mfma_f32_32x32x16_bf16 v[80:95], v[124:127], v[164:167], v[80:95]
	ds_read_b64_tr_b16 v[124:125], v188 offset:26624
	ds_read_b64_tr_b16 v[126:127], v188 offset:27136
	ds_read_b128 v[140:143], v168 offset:2048
	v_add_f32_e32 v144, v66, v144
	v_add_f32_e32 v144, v67, v144
	v_add_f32_e32 v144, v68, v144
	v_add_f32_e32 v144, v69, v144
	v_cvt_pk_bf16_f32 v148, v64, v65
	v_cvt_pk_bf16_f32 v149, v66, v67
	s_waitcnt lgkmcnt(0)
	v_mfma_f32_32x32x16_bf16 v[96:111], v[160:163], v[140:143], v[96:111]
	ds_read_b64_tr_b16 v[190:191], v188 offset:30720
	ds_read_b64_tr_b16 v[192:193], v188 offset:31232
	ds_read_b128 v[64:67], v168 offset:2048
	v_add_f32_e32 v140, v70, v144
	v_add_f32_e32 v140, v71, v140
	v_add_f32_e32 v140, v72, v140
	v_add_f32_e32 v140, v73, v140
	v_cvt_pk_bf16_f32 v150, v68, v69
	v_cvt_pk_bf16_f32 v151, v70, v71
	s_waitcnt lgkmcnt(0)
	v_mfma_f32_32x32x16_bf16 v[80:95], v[116:119], v[64:67], v[80:95]
	ds_read_b64_tr_b16 v[116:117], v188 offset:27648
	ds_read_b64_tr_b16 v[118:119], v188 offset:28160
	ds_read_b128 v[64:67], v168 offset:3072
	v_add_f32_e32 v68, v74, v140
	v_add_f32_e32 v68, v75, v68
	v_add_f32_e32 v68, v76, v68
	v_add_f32_e32 v68, v77, v68
	v_cvt_pk_bf16_f32 v144, v72, v73
	v_cvt_pk_bf16_f32 v145, v74, v75
	s_waitcnt lgkmcnt(0)
	v_mfma_f32_32x32x16_bf16 v[96:111], v[120:123], v[64:67], v[96:111]
	ds_read_b64_tr_b16 v[72:73], v188 offset:31744
	ds_read_b64_tr_b16 v[74:75], v188 offset:32256
	ds_read_b128 v[64:67], v168 offset:3072
	v_add_f32_e32 v68, v78, v68
	v_add_f32_e32 v68, v79, v68
	v_add_f32_e32 v68, 0, v68
	v_cvt_pk_bf16_f32 v146, v76, v77
	v_cvt_pk_bf16_f32 v147, v78, v79
	s_waitcnt lgkmcnt(0)
	v_mfma_f32_32x32x16_bf16 v[80:95], v[112:115], v[64:67], v[80:95]
	v_lshl_add_u64 v[64:65], v[170:171], 0, s[60:61]
	s_add_i32 s17, s85, 0xe000
	s_mov_b32 s86, m0
	s_mov_b32 m0, s17
	s_nop 0
	global_load_lds_dwordx4 v[64:65], off
	s_mov_b32 m0, s86
	v_lshl_add_u64 v[64:65], v[172:173], 0, s[60:61]
	s_add_i32 s85, s85, 0x10000
	s_mov_b32 s17, m0
	s_mov_b32 m0, s85
	s_nop 0
	global_load_lds_dwordx4 v[64:65], off
	s_mov_b32 m0, s17
	v_add_f32_e32 v174, v198, v68
	v_mfma_f32_32x32x16_bf16 v[48:63], v[156:159], v[178:181], v[48:63]
	ds_read_b64_tr_b16 v[76:77], v188 offset:32768
	ds_read_b64_tr_b16 v[78:79], v188 offset:33280
	v_exp_f32_e32 v96, v96
	v_exp_f32_e32 v97, v97
	v_mfma_f32_32x32x16_bf16 v[32:47], v[156:159], v[128:131], v[32:47]
	ds_read_b64_tr_b16 v[112:113], v188 offset:36864
	ds_read_b64_tr_b16 v[114:115], v188 offset:37376
	v_exp_f32_e32 v98, v98
	v_exp_f32_e32 v99, v99
	ds_read_b128 v[68:71], v189 offset:16384
	ds_read_b128 v[64:67], v189 offset:16896
	v_mfma_f32_32x32x16_bf16 v[48:63], v[152:155], v[132:135], v[48:63]
	ds_read_b64_tr_b16 v[120:121], v188 offset:33792
	ds_read_b64_tr_b16 v[122:123], v188 offset:34304
	v_exp_f32_e32 v100, v100
	v_exp_f32_e32 v101, v101
	ds_read_b128 v[164:167], v189 offset:18432
	ds_read_b128 v[140:143], v189 offset:18944
	v_mfma_f32_32x32x16_bf16 v[32:47], v[152:155], v[136:139], v[32:47]
	ds_read_b64_tr_b16 v[178:179], v188 offset:37888
	ds_read_b64_tr_b16 v[180:181], v188 offset:38400
	v_exp_f32_e32 v102, v102
	v_exp_f32_e32 v103, v103
	ds_read_b128 v[160:163], v189 offset:20480
	ds_read_b128 v[132:135], v189 offset:20992
	v_mfma_f32_32x32x16_bf16 v[48:63], v[148:151], v[124:127], v[48:63]
	ds_read_b64_tr_b16 v[194:195], v188 offset:34816
	ds_read_b64_tr_b16 v[196:197], v188 offset:35328
	v_exp_f32_e32 v104, v104
	v_exp_f32_e32 v105, v105
	ds_read_b128 v[136:139], v189 offset:22528
	ds_read_b128 v[128:131], v189 offset:23040
	v_mfma_f32_32x32x16_bf16 v[32:47], v[148:151], v[190:193], v[32:47]
	ds_read_b64_tr_b16 v[124:125], v188 offset:38912
	ds_read_b64_tr_b16 v[126:127], v188 offset:39424
	v_exp_f32_e32 v106, v106
	v_exp_f32_e32 v107, v107
	v_mfma_f32_32x32x16_bf16 v[48:63], v[144:147], v[116:119], v[48:63]
	ds_read_b64_tr_b16 v[190:191], v188 offset:35840
	ds_read_b64_tr_b16 v[192:193], v188 offset:36352
	v_exp_f32_e32 v108, v108
	v_exp_f32_e32 v109, v109
	v_mfma_f32_32x32x16_bf16 v[32:47], v[144:147], v[72:75], v[32:47]
	ds_read_b64_tr_b16 v[116:117], v188 offset:39936
	ds_read_b64_tr_b16 v[118:119], v188 offset:40448
	v_exp_f32_e32 v110, v110
	v_exp_f32_e32 v111, v111
	s_waitcnt lgkmcnt(14)
	v_mfma_f32_32x32x16_bf16 v[16:31], v[156:159], v[76:79], v[16:31]
	v_exp_f32_e32 v80, v80
	v_exp_f32_e32 v81, v81
	v_mfma_f32_32x32x16_bf16 v[0:15], v[156:159], v[112:115], v[0:15]
	v_exp_f32_e32 v82, v82
	v_exp_f32_e32 v83, v83
	v_mfma_f32_32x32x16_bf16 v[16:31], v[152:155], v[120:123], v[16:31]
	v_exp_f32_e32 v84, v84
	v_exp_f32_e32 v85, v85
	s_waitcnt lgkmcnt(12)
	v_mfma_f32_32x32x16_bf16 v[0:15], v[152:155], v[178:181], v[0:15]
	v_exp_f32_e32 v86, v86
	v_exp_f32_e32 v87, v87
	s_waitcnt lgkmcnt(8)
	v_mfma_f32_32x32x16_bf16 v[16:31], v[148:151], v[194:197], v[16:31]
	v_exp_f32_e32 v88, v88
	v_exp_f32_e32 v89, v89
	s_waitcnt lgkmcnt(4)
	v_mfma_f32_32x32x16_bf16 v[0:15], v[148:151], v[124:127], v[0:15]
	v_exp_f32_e32 v90, v90
	v_exp_f32_e32 v91, v91
	s_waitcnt lgkmcnt(2)
	v_mfma_f32_32x32x16_bf16 v[16:31], v[144:147], v[190:193], v[16:31]
	v_exp_f32_e32 v92, v92
	v_exp_f32_e32 v93, v93
	s_waitcnt lgkmcnt(0)
	v_mfma_f32_32x32x16_bf16 v[0:15], v[144:147], v[116:119], v[0:15]
	v_exp_f32_e32 v94, v94
	v_exp_f32_e32 v95, v95
	s_waitcnt vmcnt(2) lgkmcnt(0)
	s_barrier
; #define WAIT_BAR(N) asm volatile("s_waitcnt vmcnt(" #N ") lgkmcnt(0)\n\ts_barrier":::"memory")
;   #define RESC() do{ if(!NOMAX&&resc){ asm volatile("s_waitcnt lgkmcnt(0)":::"memory"); \
;       _Pragma("unroll") for(int d_=0;d_<2*VM;++d_) _Pragma("unroll") for(int r=0;r<16;++r)o[d_][r]*=wsf[crow(r,hi)]; } }while(0)
;   #define ROT() do{sl_prev=sl_cur;sl_cur=sl_next;sl_next=(sl_next==(NSLOT-1)*SLOTB)?0:sl_next+SLOTB;}while(0)
;   #define ENDW(tt) do{ if((tt)+3<NT){ if constexpr(VM==2){WAIT_BAR(3);}else{WAIT_BAR(2);} } else if((tt)+2<NT){ if constexpr(VM==2){WAIT_BAR(2);}else{WAIT_BAR(1);} } else {WAIT_BAR(0);} }while(0)
; template<int THRL,int VM,bool NOMAX> __device__ __forceinline__ void attn_unit(const bf16*Qb,const bf16*__restrict__ Kh,const bf16*__restrict__ Vh,bf16*Ob,const int NT,const int sp,float*wscr,char*shm){
;     ...
;   int t=1;
;   for(;t+5<NT;t+=2){
;     STEP(pB0,pB1,pA0,pA1,t,true,true,true);     if constexpr(VM==2){WAIT_BAR(3);}else{WAIT_BAR(2);} RESC(); ROT();
;     STEP(pA0,pA1,pB0,pB1,t+1,true,true,true);   if constexpr(VM==2){WAIT_BAR(3);}else{WAIT_BAR(2);} RESC(); ROT();
;   }
;     ...
;   for(;t+1<NT;t+=2){
;     STEP(pB0,pB1,pA0,pA1,t,(t+3<NT),(t+1<NT),(t+1<NT));       ENDW(t);   RESC(); ROT();
;     STEP(pA0,pA1,pB0,pB1,t+1,(t+4<NT),(t+2<NT),(t+2<NT));     ENDW(t+1); RESC(); ROT();
	ds_read_b64_tr_b16 v[178:179], v188 offset:40960
	ds_read_b64_tr_b16 v[180:181], v188 offset:41472
	v_add_f32_e32 v76, v96, v97
	ds_read_b128 v[72:75], v168
	v_add_f32_e32 v76, v98, v76
	v_add_f32_e32 v76, v99, v76
	v_add_f32_e32 v76, v100, v76
	v_add_f32_e32 v76, v101, v76
	v_cvt_pk_bf16_f32 v156, v96, v97
	v_cvt_pk_bf16_f32 v157, v98, v99
	s_waitcnt lgkmcnt(0)
	v_mfma_f32_32x32x16_bf16 v[112:127], v[68:71], v[72:75], 0
	ds_read_b64_tr_b16 v[96:97], v188 offset:45056
	ds_read_b64_tr_b16 v[98:99], v188 offset:45568
	ds_read_b128 v[68:71], v168
	v_add_f32_e32 v72, v102, v76
	v_add_f32_e32 v72, v103, v72
	v_add_f32_e32 v72, v104, v72
	v_add_f32_e32 v144, v105, v72
	s_waitcnt lgkmcnt(0)
	v_mfma_f32_32x32x16_bf16 v[64:79], v[64:67], v[68:71], 0
	v_cvt_pk_bf16_f32 v158, v100, v101
	v_cvt_pk_bf16_f32 v159, v102, v103
	ds_read_b64_tr_b16 v[100:101], v188 offset:41984
	ds_read_b64_tr_b16 v[102:103], v188 offset:42496
	ds_read_b128 v[190:193], v168 offset:1024
	v_add_f32_e32 v144, v106, v144
	v_add_f32_e32 v144, v107, v144
	v_add_f32_e32 v144, v108, v144
	v_add_f32_e32 v144, v109, v144
	v_cvt_pk_bf16_f32 v152, v104, v105
	v_cvt_pk_bf16_f32 v153, v106, v107
	s_waitcnt lgkmcnt(0)
	v_mfma_f32_32x32x16_bf16 v[112:127], v[164:167], v[190:193], v[112:127]
	ds_read_b64_tr_b16 v[104:105], v188 offset:46080
	ds_read_b64_tr_b16 v[106:107], v188 offset:46592
	ds_read_b128 v[164:167], v168 offset:1024
	v_add_f32_e32 v144, v110, v144
	v_add_f32_e32 v144, v111, v144
	v_add_f32_e32 v144, v80, v144
	v_add_f32_e32 v144, v81, v144
	s_waitcnt lgkmcnt(0)
	v_mfma_f32_32x32x16_bf16 v[64:79], v[140:143], v[164:167], v[64:79]
	v_cvt_pk_bf16_f32 v154, v108, v109
	v_cvt_pk_bf16_f32 v155, v110, v111
	ds_read_b64_tr_b16 v[108:109], v188 offset:43008
	ds_read_b64_tr_b16 v[110:111], v188 offset:43520
	ds_read_b128 v[140:143], v168 offset:2048
	v_add_f32_e32 v144, v82, v144
	v_add_f32_e32 v144, v83, v144
	v_add_f32_e32 v144, v84, v144
	v_add_f32_e32 v144, v85, v144
	v_cvt_pk_bf16_f32 v148, v80, v81
	v_cvt_pk_bf16_f32 v149, v82, v83
	s_waitcnt lgkmcnt(0)
	v_mfma_f32_32x32x16_bf16 v[112:127], v[160:163], v[140:143], v[112:127]
	ds_read_b64_tr_b16 v[190:191], v188 offset:47104
	ds_read_b64_tr_b16 v[192:193], v188 offset:47616
	ds_read_b128 v[80:83], v168 offset:2048
	v_add_f32_e32 v140, v86, v144
	v_add_f32_e32 v140, v87, v140
	v_add_f32_e32 v140, v88, v140
	v_add_f32_e32 v140, v89, v140
	s_waitcnt lgkmcnt(0)
	v_mfma_f32_32x32x16_bf16 v[64:79], v[132:135], v[80:83], v[64:79]
	v_cvt_pk_bf16_f32 v150, v84, v85
	v_cvt_pk_bf16_f32 v151, v86, v87
	ds_read_b64_tr_b16 v[84:85], v188 offset:44032
	ds_read_b64_tr_b16 v[86:87], v188 offset:44544
	ds_read_b128 v[80:83], v168 offset:3072
	v_add_f32_e32 v132, v90, v140
	v_add_f32_e32 v132, v91, v132
	v_add_f32_e32 v132, v92, v132
	v_add_f32_e32 v132, v93, v132
	v_cvt_pk_bf16_f32 v144, v88, v89
	v_cvt_pk_bf16_f32 v145, v90, v91
	s_waitcnt lgkmcnt(0)
	v_mfma_f32_32x32x16_bf16 v[112:127], v[136:139], v[80:83], v[112:127]
	ds_read_b64_tr_b16 v[88:89], v188 offset:48128
	ds_read_b64_tr_b16 v[90:91], v188 offset:48640
	ds_read_b128 v[80:83], v168 offset:3072
	v_add_f32_e32 v132, v94, v132
	v_add_f32_e32 v132, v95, v132
	v_add_f32_e32 v132, 0, v132
	v_cvt_pk_bf16_f32 v146, v92, v93
	s_waitcnt lgkmcnt(0)
	v_mfma_f32_32x32x16_bf16 v[64:79], v[128:131], v[80:83], v[64:79]
	v_cvt_pk_bf16_f32 v147, v94, v95
	v_lshl_add_u64 v[80:81], v[170:171], 0, s[64:65]
	s_mov_b32 s17, m0
	s_mov_b32 m0, s16
	s_nop 0
	global_load_lds_dwordx4 v[80:81], off
	s_mov_b32 m0, s17
	v_lshl_add_u64 v[80:81], v[172:173], 0, s[64:65]
	s_mov_b32 s16, m0
	s_mov_b32 m0, s35
	s_nop 0
	global_load_lds_dwordx4 v[80:81], off
	s_mov_b32 m0, s16
	v_add_f32_e32 v174, v174, v132
	v_mfma_f32_32x32x16_bf16 v[48:63], v[156:159], v[178:181], v[48:63]
	ds_read_b64_tr_b16 v[92:93], v188 offset:49152
	ds_read_b64_tr_b16 v[94:95], v188 offset:49664
	v_exp_f32_e32 v112, v112
	v_exp_f32_e32 v113, v113
	v_mfma_f32_32x32x16_bf16 v[32:47], v[156:159], v[96:99], v[32:47]
	ds_read_b64_tr_b16 v[170:171], v188 offset:53248
	ds_read_b64_tr_b16 v[172:173], v188 offset:53760
	v_exp_f32_e32 v114, v114
	v_exp_f32_e32 v115, v115
	ds_read_b128 v[80:83], v189
	ds_read_b128 v[96:99], v189 offset:512
	v_mfma_f32_32x32x16_bf16 v[48:63], v[152:155], v[100:103], v[48:63]
	ds_read_b64_tr_b16 v[178:179], v188 offset:50176
	ds_read_b64_tr_b16 v[180:181], v188 offset:50688
	v_exp_f32_e32 v116, v116
	v_exp_f32_e32 v117, v117
	ds_read_b128 v[164:167], v189 offset:2048
	ds_read_b128 v[140:143], v189 offset:2560
	v_mfma_f32_32x32x16_bf16 v[32:47], v[152:155], v[104:107], v[32:47]
	ds_read_b64_tr_b16 v[100:101], v188 offset:54272
	ds_read_b64_tr_b16 v[102:103], v188 offset:54784
	v_exp_f32_e32 v118, v118
	v_exp_f32_e32 v119, v119
	ds_read_b128 v[160:163], v189 offset:4096
	ds_read_b128 v[132:135], v189 offset:4608
	v_mfma_f32_32x32x16_bf16 v[48:63], v[148:151], v[108:111], v[48:63]
	ds_read_b64_tr_b16 v[104:105], v188 offset:51200
	ds_read_b64_tr_b16 v[106:107], v188 offset:51712
	v_exp_f32_e32 v120, v120
	v_exp_f32_e32 v121, v121
	ds_read_b128 v[136:139], v189 offset:6144
	ds_read_b128 v[128:131], v189 offset:6656
	v_mfma_f32_32x32x16_bf16 v[32:47], v[148:151], v[190:193], v[32:47]
	ds_read_b64_tr_b16 v[108:109], v188 offset:55296
	ds_read_b64_tr_b16 v[110:111], v188 offset:55808
	v_exp_f32_e32 v122, v122
	v_exp_f32_e32 v123, v123
	v_mfma_f32_32x32x16_bf16 v[48:63], v[144:147], v[84:87], v[48:63]
	ds_read_b64_tr_b16 v[190:191], v188 offset:52224
	ds_read_b64_tr_b16 v[192:193], v188 offset:52736
	v_exp_f32_e32 v124, v124
	v_exp_f32_e32 v125, v125
	v_mfma_f32_32x32x16_bf16 v[32:47], v[144:147], v[88:91], v[32:47]
	ds_read_b64_tr_b16 v[84:85], v188 offset:56320
	ds_read_b64_tr_b16 v[86:87], v188 offset:56832
	v_exp_f32_e32 v126, v126
	v_exp_f32_e32 v127, v127
	s_waitcnt lgkmcnt(14)
	v_mfma_f32_32x32x16_bf16 v[16:31], v[156:159], v[92:95], v[16:31]
	v_exp_f32_e32 v64, v64
	v_exp_f32_e32 v65, v65
	v_mfma_f32_32x32x16_bf16 v[0:15], v[156:159], v[170:173], v[0:15]
	v_exp_f32_e32 v66, v66
	v_exp_f32_e32 v67, v67
	v_mfma_f32_32x32x16_bf16 v[16:31], v[152:155], v[178:181], v[16:31]
	v_exp_f32_e32 v68, v68
	v_exp_f32_e32 v69, v69
	s_waitcnt lgkmcnt(12)
	v_mfma_f32_32x32x16_bf16 v[0:15], v[152:155], v[100:103], v[0:15]
	v_exp_f32_e32 v70, v70
	v_exp_f32_e32 v71, v71
	s_waitcnt lgkmcnt(8)
	v_mfma_f32_32x32x16_bf16 v[16:31], v[148:151], v[104:107], v[16:31]
	v_exp_f32_e32 v72, v72
	v_exp_f32_e32 v73, v73
	s_waitcnt lgkmcnt(4)
	v_mfma_f32_32x32x16_bf16 v[0:15], v[148:151], v[108:111], v[0:15]
	v_exp_f32_e32 v74, v74
	v_exp_f32_e32 v75, v75
	s_waitcnt lgkmcnt(2)
	v_mfma_f32_32x32x16_bf16 v[16:31], v[144:147], v[190:193], v[16:31]
	v_exp_f32_e32 v76, v76
	v_exp_f32_e32 v77, v77
	s_waitcnt lgkmcnt(0)
	v_mfma_f32_32x32x16_bf16 v[0:15], v[144:147], v[84:87], v[0:15]
	v_exp_f32_e32 v78, v78
	v_exp_f32_e32 v79, v79
	s_waitcnt vmcnt(0) lgkmcnt(0)
	s_barrier
	ds_read_b64_tr_b16 v[170:171], v188 offset:57344
	ds_read_b64_tr_b16 v[172:173], v188 offset:57856
	v_add_f32_e32 v88, v112, v113
	ds_read_b128 v[84:87], v168
	v_add_f32_e32 v88, v114, v88
	v_add_f32_e32 v88, v115, v88
	v_add_f32_e32 v88, v116, v88
	v_add_f32_e32 v104, v117, v88
	v_cvt_pk_bf16_f32 v156, v112, v113
	v_cvt_pk_bf16_f32 v157, v114, v115
	s_waitcnt lgkmcnt(0)
	v_mfma_f32_32x32x16_bf16 v[80:95], v[80:83], v[84:87], 0
	ds_read_b64_tr_b16 v[112:113], v188 offset:61440
	ds_read_b64_tr_b16 v[114:115], v188 offset:61952
	ds_read_b128 v[100:103], v168
	v_add_f32_e32 v104, v118, v104
	v_add_f32_e32 v104, v119, v104
	v_add_f32_e32 v104, v120, v104
	v_add_f32_e32 v144, v121, v104
	v_cvt_pk_bf16_f32 v158, v116, v117
	v_cvt_pk_bf16_f32 v159, v118, v119
	s_waitcnt lgkmcnt(0)
	v_mfma_f32_32x32x16_bf16 v[96:111], v[96:99], v[100:103], 0
	ds_read_b64_tr_b16 v[116:117], v188 offset:58368
	ds_read_b64_tr_b16 v[118:119], v188 offset:58880
	ds_read_b128 v[178:181], v168 offset:1024
	v_add_f32_e32 v144, v122, v144
	v_add_f32_e32 v144, v123, v144
	v_add_f32_e32 v144, v124, v144
	v_add_f32_e32 v144, v125, v144
	v_cvt_pk_bf16_f32 v152, v120, v121
	v_cvt_pk_bf16_f32 v153, v122, v123
	s_waitcnt lgkmcnt(0)
	v_mfma_f32_32x32x16_bf16 v[80:95], v[164:167], v[178:181], v[80:95]
	ds_read_b64_tr_b16 v[120:121], v188 offset:62464
	ds_read_b64_tr_b16 v[122:123], v188 offset:62976
	ds_read_b128 v[164:167], v168 offset:1024
	v_add_f32_e32 v144, v126, v144
	v_add_f32_e32 v144, v127, v144
	v_add_f32_e32 v144, v64, v144
	v_add_f32_e32 v144, v65, v144
	v_cvt_pk_bf16_f32 v154, v124, v125
	v_cvt_pk_bf16_f32 v155, v126, v127
	s_waitcnt lgkmcnt(0)
	v_mfma_f32_32x32x16_bf16 v[96:111], v[140:143], v[164:167], v[96:111]
	ds_read_b64_tr_b16 v[124:125], v188 offset:59392
	ds_read_b64_tr_b16 v[126:127], v188 offset:59904
	ds_read_b128 v[140:143], v168 offset:2048
	v_add_f32_e32 v144, v66, v144
	v_add_f32_e32 v144, v67, v144
	v_add_f32_e32 v144, v68, v144
	v_add_f32_e32 v144, v69, v144
	v_cvt_pk_bf16_f32 v148, v64, v65
	v_cvt_pk_bf16_f32 v149, v66, v67
	s_waitcnt lgkmcnt(0)
	v_mfma_f32_32x32x16_bf16 v[80:95], v[160:163], v[140:143], v[80:95]
	ds_read_b64_tr_b16 v[64:65], v188 offset:63488
	ds_read_b64_tr_b16 v[66:67], v188 offset:64000
	ds_read_b128 v[140:143], v168 offset:2048
	v_add_f32_e32 v144, v70, v144
	v_add_f32_e32 v144, v71, v144
	v_add_f32_e32 v144, v72, v144
	v_add_f32_e32 v144, v73, v144
	v_cvt_pk_bf16_f32 v150, v68, v69
	v_cvt_pk_bf16_f32 v151, v70, v71
	s_waitcnt lgkmcnt(0)
	v_mfma_f32_32x32x16_bf16 v[96:111], v[132:135], v[140:143], v[96:111]
	ds_read_b64_tr_b16 v[68:69], v188 offset:60416
	ds_read_b64_tr_b16 v[70:71], v188 offset:60928
	ds_read_b128 v[132:135], v168 offset:3072
	v_add_f32_e32 v140, v74, v144
	v_add_f32_e32 v140, v75, v140
	v_add_f32_e32 v140, v76, v140
	v_add_f32_e32 v140, v77, v140
	v_cvt_pk_bf16_f32 v144, v72, v73
	v_cvt_pk_bf16_f32 v145, v74, v75
	s_waitcnt lgkmcnt(0)
	v_mfma_f32_32x32x16_bf16 v[80:95], v[136:139], v[132:135], v[80:95]
	ds_read_b64_tr_b16 v[72:73], v188 offset:64512
	ds_read_b64_tr_b16 v[74:75], v188 offset:65024
	ds_read_b128 v[132:135], v168 offset:3072
	v_add_f32_e32 v136, v78, v140
	v_add_f32_e32 v136, v79, v136
	v_add_f32_e32 v136, 0, v136
	v_cvt_pk_bf16_f32 v146, v76, v77
	v_cvt_pk_bf16_f32 v147, v78, v79
	s_waitcnt lgkmcnt(0)
	v_mfma_f32_32x32x16_bf16 v[96:111], v[128:131], v[132:135], v[96:111]
	v_mfma_f32_32x32x16_bf16 v[48:63], v[156:159], v[170:173], v[48:63]
	ds_read_b64_tr_b16 v[76:77], v177 offset:40960
	ds_read_b64_tr_b16 v[78:79], v177 offset:41472
	v_exp_f32_e32 v80, v80
	v_exp_f32_e32 v81, v81
	v_mfma_f32_32x32x16_bf16 v[32:47], v[156:159], v[112:115], v[32:47]
	ds_read_b64_tr_b16 v[128:129], v177 offset:45056
	ds_read_b64_tr_b16 v[130:131], v177 offset:45568
	v_exp_f32_e32 v82, v82
	v_exp_f32_e32 v83, v83
	v_mfma_f32_32x32x16_bf16 v[48:63], v[152:155], v[116:119], v[48:63]
	ds_read_b64_tr_b16 v[112:113], v177 offset:41984
	ds_read_b64_tr_b16 v[114:115], v177 offset:42496
	v_exp_f32_e32 v84, v84
	v_exp_f32_e32 v85, v85
	v_mfma_f32_32x32x16_bf16 v[32:47], v[152:155], v[120:123], v[32:47]
	ds_read_b64_tr_b16 v[116:117], v177 offset:46080
	ds_read_b64_tr_b16 v[118:119], v177 offset:46592
	v_exp_f32_e32 v86, v86
	v_exp_f32_e32 v87, v87
	v_mfma_f32_32x32x16_bf16 v[48:63], v[148:151], v[124:127], v[48:63]
	ds_read_b64_tr_b16 v[120:121], v177 offset:43008
	ds_read_b64_tr_b16 v[122:123], v177 offset:43520
	v_exp_f32_e32 v88, v88
	v_exp_f32_e32 v89, v89
	v_mfma_f32_32x32x16_bf16 v[32:47], v[148:151], v[64:67], v[32:47]
	ds_read_b64_tr_b16 v[124:125], v177 offset:47104
	ds_read_b64_tr_b16 v[126:127], v177 offset:47616
	v_exp_f32_e32 v90, v90
	v_exp_f32_e32 v91, v91
	v_mfma_f32_32x32x16_bf16 v[48:63], v[144:147], v[68:71], v[48:63]
	ds_read_b64_tr_b16 v[64:65], v177 offset:44032
	ds_read_b64_tr_b16 v[66:67], v177 offset:44544
	v_exp_f32_e32 v92, v92
	v_exp_f32_e32 v93, v93
	v_mfma_f32_32x32x16_bf16 v[32:47], v[144:147], v[72:75], v[32:47]
	ds_read_b64_tr_b16 v[68:69], v177 offset:48128
	ds_read_b64_tr_b16 v[70:71], v177 offset:48640
	v_exp_f32_e32 v94, v94
	v_exp_f32_e32 v95, v95
	s_waitcnt lgkmcnt(14)
	v_mfma_f32_32x32x16_bf16 v[16:31], v[156:159], v[76:79], v[16:31]
	v_exp_f32_e32 v96, v96
	v_exp_f32_e32 v97, v97
	s_waitcnt lgkmcnt(12)
; #define SBAR() __builtin_amdgcn_sched_barrier(0)
; #define WAIT_BAR(N) asm volatile("s_waitcnt vmcnt(" #N ") lgkmcnt(0)\n\ts_barrier":::"memory")
;   #define ROT() do{sl_prev=sl_cur;sl_cur=sl_next;sl_next=(sl_next==(NSLOT-1)*SLOTB)?0:sl_next+SLOTB;}while(0)
; __device__ __forceinline__ void pv(f32x16*o,int vb,bf16x8 pa0,bf16x8 pa1,bf16x8 pa2,bf16x8 pa3){
;   #pragma unroll
;   for(int d0=0;d0<2;++d0){s16x4 lo[4],hi[4];
;     #pragma unroll
;     for(int ks=0;ks<4;++ks){
;       asm volatile("ds_read_b64_tr_b16 %0,%1 offset:%c2":"=&v"(lo[ks]):"v"(vb),"i"(d0*4096+ks*1024):"memory");
;       asm volatile("ds_read_b64_tr_b16 %0,%1 offset:%c2":"=&v"(hi[ks]):"v"(vb),"i"(d0*4096+ks*1024+512):"memory");}
;     asm volatile("s_waitcnt lgkmcnt(0)":::"memory");SBAR();
;     ...
;     o[d0]=__builtin_amdgcn_mfma_f32_32x32x16_bf16(pa0,PK(0),o[d0],0,0,0);
;     o[d0]=__builtin_amdgcn_mfma_f32_32x32x16_bf16(pa1,PK(1),o[d0],0,0,0);
;     o[d0]=__builtin_amdgcn_mfma_f32_32x32x16_bf16(pa2,PK(2),o[d0],0,0,0);
;     o[d0]=__builtin_amdgcn_mfma_f32_32x32x16_bf16(pa3,PK(3),o[d0],0,0,0);
;     ...
;   }
; }
; template<int THRL,int VM,bool NOMAX> __device__ __forceinline__ void attn_unit(const bf16*Qb,const bf16*__restrict__ Kh,const bf16*__restrict__ Vh,bf16*Ob,const int NT,const int sp,float*wscr,char*shm){
;     ...
;   int t=1;
;   for(;t+5<NT;t+=2){
;     STEP(pB0,pB1,pA0,pA1,t,true,true,true);     if constexpr(VM==2){WAIT_BAR(3);}else{WAIT_BAR(2);} RESC(); ROT();
;     STEP(pA0,pA1,pB0,pB1,t+1,true,true,true);   if constexpr(VM==2){WAIT_BAR(3);}else{WAIT_BAR(2);} RESC(); ROT();
;   }
;     ...
;   for(;t+1<NT;t+=2){
;     STEP(pB0,pB1,pA0,pA1,t,(t+3<NT),(t+1<NT),(t+1<NT));       ENDW(t);   RESC(); ROT();
;     STEP(pA0,pA1,pB0,pB1,t+1,(t+4<NT),(t+2<NT),(t+2<NT));     ENDW(t+1); RESC(); ROT();
;   }
;   STEP(pB0,pB1,pA0,pA1,NT-1,false,false,false); RESC();
;   { float sacc=pB0[0]+pB0[1]; _Pragma("unroll") for(int r=2;r<16;++r)sacc+=pB0[r]; _Pragma("unroll") for(int r=0;r<16;++r)sacc+=pB1[r]; l_reg+=sacc;
;     pw0=(u32x4){PKW(pB0,0),PKW(pB0,2),PKW(pB0,4),PKW(pB0,6)};pw1=(u32x4){PKW(pB0,8),PKW(pB0,10),PKW(pB0,12),PKW(pB0,14)};pw2=(u32x4){PKW(pB1,0),PKW(pB1,2),PKW(pB1,4),PKW(pB1,6)};pw3=(u32x4){PKW(pB1,8),PKW(pB1,10),PKW(pB1,12),PKW(pB1,14)};
;     SBAR(); pv(o,vb0+VM*sl_cur,PAF(0),PAF(1),PAF(2),PAF(3)); if constexpr(VM==2) pv(o+2,vb0+VM*sl_cur+8192,PAF(0),PAF(1),PAF(2),PAF(3)); }
	v_mfma_f32_32x32x16_bf16 v[0:15], v[156:159], v[128:131], v[0:15]
	v_exp_f32_e32 v98, v98
	v_exp_f32_e32 v99, v99
	s_waitcnt lgkmcnt(10)
	v_mfma_f32_32x32x16_bf16 v[16:31], v[152:155], v[112:115], v[16:31]
	v_exp_f32_e32 v100, v100
	v_exp_f32_e32 v101, v101
	s_waitcnt lgkmcnt(8)
	v_mfma_f32_32x32x16_bf16 v[0:15], v[152:155], v[116:119], v[0:15]
	v_exp_f32_e32 v102, v102
	v_exp_f32_e32 v103, v103
	s_waitcnt lgkmcnt(6)
	v_mfma_f32_32x32x16_bf16 v[16:31], v[148:151], v[120:123], v[16:31]
	v_exp_f32_e32 v104, v104
	v_exp_f32_e32 v105, v105
	s_waitcnt lgkmcnt(4)
	v_mfma_f32_32x32x16_bf16 v[0:15], v[148:151], v[124:127], v[0:15]
	v_exp_f32_e32 v106, v106
	v_exp_f32_e32 v107, v107
	s_waitcnt lgkmcnt(2)
	v_mfma_f32_32x32x16_bf16 v[16:31], v[144:147], v[64:67], v[16:31]
	v_exp_f32_e32 v108, v108
	v_exp_f32_e32 v109, v109
	s_waitcnt lgkmcnt(0)
	v_mfma_f32_32x32x16_bf16 v[0:15], v[144:147], v[68:71], v[0:15]
	v_exp_f32_e32 v110, v110
	v_exp_f32_e32 v111, v111
	v_add_f32_e32 v64, v80, v81
	v_add_f32_e32 v64, v82, v64
	v_add_f32_e32 v64, v83, v64
	v_add_f32_e32 v64, v84, v64
	v_add_f32_e32 v64, v85, v64
	v_add_f32_e32 v64, v86, v64
	v_add_f32_e32 v64, v87, v64
	v_add_f32_e32 v64, v88, v64
	v_add_f32_e32 v64, v89, v64
	v_add_f32_e32 v64, v90, v64
	v_add_f32_e32 v64, v91, v64
	v_add_f32_e32 v64, v92, v64
	v_add_f32_e32 v64, v93, v64
	v_add_f32_e32 v64, v94, v64
	v_add_f32_e32 v64, v95, v64
	v_add_f32_e32 v64, v64, v96
	v_add_f32_e32 v64, v97, v64
	v_add_f32_e32 v64, v98, v64
	v_add_f32_e32 v64, v99, v64
	v_add_f32_e32 v64, v100, v64
	v_add_f32_e32 v64, v101, v64
	v_add_f32_e32 v64, v102, v64
	v_add_f32_e32 v64, v103, v64
	v_add_f32_e32 v64, v104, v64
	v_add_f32_e32 v64, v105, v64
	v_add_f32_e32 v64, v106, v64
	v_add_f32_e32 v64, v107, v64
	v_add_f32_e32 v64, v108, v64
	v_add_f32_e32 v64, v109, v64
	v_add_f32_e32 v64, v110, v64
	v_add_f32_e32 v64, v111, v64
	v_add_f32_e32 v65, v174, v136
	v_add_f32_e32 v64, v65, v64
	v_cvt_pk_bf16_f32 v66, v80, v81
	v_cvt_pk_bf16_f32 v67, v82, v83
	v_cvt_pk_bf16_f32 v68, v84, v85
	v_cvt_pk_bf16_f32 v69, v86, v87
	v_cvt_pk_bf16_f32 v70, v88, v89
	v_cvt_pk_bf16_f32 v71, v90, v91
	v_cvt_pk_bf16_f32 v72, v92, v93
	v_cvt_pk_bf16_f32 v73, v94, v95
	v_cvt_pk_bf16_f32 v74, v96, v97
	v_cvt_pk_bf16_f32 v75, v98, v99
	v_cvt_pk_bf16_f32 v76, v100, v101
	v_cvt_pk_bf16_f32 v77, v102, v103
	v_cvt_pk_bf16_f32 v78, v104, v105
	v_cvt_pk_bf16_f32 v79, v106, v107
	v_cvt_pk_bf16_f32 v80, v108, v109
	v_cvt_pk_bf16_f32 v81, v110, v111
	ds_read_b64_tr_b16 v[82:83],v176 offset:0
	ds_read_b64_tr_b16 v[84:85],v176 offset:512
	ds_read_b64_tr_b16 v[86:87],v176 offset:1024
	ds_read_b64_tr_b16 v[88:89],v176 offset:1536
	ds_read_b64_tr_b16 v[90:91],v176 offset:2048
	ds_read_b64_tr_b16 v[92:93],v176 offset:2560
	ds_read_b64_tr_b16 v[94:95],v176 offset:3072
	ds_read_b64_tr_b16 v[96:97],v176 offset:3584
	s_waitcnt lgkmcnt(0)
	s_nop 0
	v_mfma_f32_32x32x16_bf16 v[48:63], v[66:69], v[82:85], v[48:63]
	ds_read_b64_tr_b16 v[82:83],v176 offset:4096
	ds_read_b64_tr_b16 v[84:85],v176 offset:4608
	v_mfma_f32_32x32x16_bf16 v[48:63], v[70:73], v[86:89], v[48:63]
	ds_read_b64_tr_b16 v[86:87],v176 offset:5120
	ds_read_b64_tr_b16 v[88:89],v176 offset:5632
	v_mfma_f32_32x32x16_bf16 v[48:63], v[74:77], v[90:93], v[48:63]
	ds_read_b64_tr_b16 v[90:91],v176 offset:6144
	ds_read_b64_tr_b16 v[92:93],v176 offset:6656
	ds_read_b64_tr_b16 v[98:99],v176 offset:7168
	ds_read_b64_tr_b16 v[100:101],v176 offset:7680
	s_waitcnt lgkmcnt(0)
	v_mfma_f32_32x32x16_bf16 v[48:63], v[78:81], v[94:97], v[48:63]
	v_mfma_f32_32x32x16_bf16 v[32:47], v[66:69], v[82:85], v[32:47]
	v_add_u32_e32 v65, 0x2000, v176
	ds_read_b64_tr_b16 v[82:83],v65 offset:0
	ds_read_b64_tr_b16 v[84:85],v65 offset:512
	v_mfma_f32_32x32x16_bf16 v[32:47], v[70:73], v[86:89], v[32:47]
	ds_read_b64_tr_b16 v[86:87],v65 offset:1024
	ds_read_b64_tr_b16 v[88:89],v65 offset:1536
	v_mfma_f32_32x32x16_bf16 v[32:47], v[74:77], v[90:93], v[32:47]
	ds_read_b64_tr_b16 v[90:91],v65 offset:2048
	ds_read_b64_tr_b16 v[92:93],v65 offset:2560
	ds_read_b64_tr_b16 v[94:95],v65 offset:3072
	ds_read_b64_tr_b16 v[96:97],v65 offset:3584
	s_waitcnt lgkmcnt(0)
	v_mfma_f32_32x32x16_bf16 v[32:47], v[78:81], v[98:101], v[32:47]
	v_mfma_f32_32x32x16_bf16 v[16:31], v[66:69], v[82:85], v[16:31]
	ds_read_b64_tr_b16 v[82:83],v65 offset:4096
	ds_read_b64_tr_b16 v[84:85],v65 offset:4608
	v_mfma_f32_32x32x16_bf16 v[16:31], v[70:73], v[86:89], v[16:31]
	ds_read_b64_tr_b16 v[86:87],v65 offset:5120
	ds_read_b64_tr_b16 v[88:89],v65 offset:5632
	v_mfma_f32_32x32x16_bf16 v[16:31], v[74:77], v[90:93], v[16:31]
	ds_read_b64_tr_b16 v[90:91],v65 offset:6144
	ds_read_b64_tr_b16 v[92:93],v65 offset:6656
	ds_read_b64_tr_b16 v[98:99],v65 offset:7168
	ds_read_b64_tr_b16 v[100:101],v65 offset:7680
	s_waitcnt lgkmcnt(0)
	v_mfma_f32_32x32x16_bf16 v[16:31], v[78:81], v[94:97], v[16:31]
	v_mfma_f32_32x32x16_bf16 v[0:15], v[66:69], v[82:85], v[0:15]
	v_mov_b32_e32 v65, v64
	s_nop 1
	v_permlane32_swap_b32_e32 v64, v65
	v_cmp_gt_u32_e32 vcc, 32, v187
	v_mfma_f32_32x32x16_bf16 v[0:15], v[70:73], v[86:89], v[0:15]
	v_mfma_f32_32x32x16_bf16 v[0:15], v[74:77], v[90:93], v[0:15]
	v_mfma_f32_32x32x16_bf16 v[0:15], v[78:81], v[98:101], v[0:15]
	s_and_saveexec_b64 s[16:17], vcc
	s_cbranch_execz .LBB0_870
	v_add_f32_e32 v64, v64, v65
	v_lshl_add_u32 v65, v186, 2, s34
	ds_write_b32 v65, v64 offset:128
	s_branch .LBB0_870
